# as before plus priority raised for load segments (flipped s_setprio)
# baseline (speedup 1.0000x reference)
; #define PG8_STAGE(bufoff, gbase, voff) do { _Pragma("unroll") for (int _i = 0; _i < 2; ++_i) \
;         __builtin_amdgcn_global_load_lds((const unsigned*)((const char*)(gbase) + (voff)[_i]), (PG8_LAS unsigned*)(lds + (bufoff) + ldsw + _i * 8192), 16, 0, 0); } while (0)
; #define PG8_LDA(dst, b, h) do { _Pragma("unroll") for (int m = 0; m < 4; ++m) _Pragma("unroll") for (int k = 0; k < 2; ++k) dst[m][k] = *(const PG8_LAS bf16x8*)(lds + PG8_SA(b, h) + aoff + m * 2048 + k * 1024); } while (0)
; #define PG8_LDB(dst, b, h) do { _Pragma("unroll") for (int n = 0; n < 2; ++n) _Pragma("unroll") for (int k = 0; k < 2; ++k) dst[n][k] = *(const PG8_LAS bf16x8*)(lds + PG8_SB(b, h) + boff + n * 2048 + k * 1024); } while (0)
; #define PG8_MMA(ai, bj, At, Bt) do { __builtin_amdgcn_s_setprio(1); _Pragma("unroll") for (int m = 0; m < 4; ++m) _Pragma("unroll") for (int n = 0; n < 2; ++n) _Pragma("unroll") for (int k = 0; k < 2; ++k) \
;         acc[ai][bj][m][n] = __builtin_amdgcn_mfma_f32_16x16x32_bf16(Bt[n][k], At[m][k], acc[ai][bj][m][n], 0, 0, 0); __builtin_amdgcn_s_setprio(0); } while (0)
; #define PG8_WAIT_V(n) asm volatile("s_waitcnt vmcnt(" #n ")" ::: "memory")
; #define PG8_BAR __builtin_amdgcn_s_barrier()
; template <class Epi, class Sched, bool ALIGN_EPI = false, bool SP2 = false>
; __device__ __forceinline__ void gemm_phase(PG8_LAS unsigned char* lds, const Gemm g, const Sched& S, const Epi& E) {
;     ...
;         for (int t = 0; t < nt; t += 2) {
;             const bool last = (t == nt - 2);
;             const char* a1 = cA + (size_t)(t + 1) * kstep;
;             const char* a2 = last ? nA : cA + (size_t)(t + 2) * kstep; const char* b2 = last ? nB : cB + (size_t)(t + 2) * kstep;
;             const char* a3 = a2 + kstep; const char* b3 = b2 + kstep;
;             if (last && has_next) S.a_ready(nxt);
;             if constexpr (SP2) {
;             PG8_LDB(B0, 0, 0); PG8_LDB(B1, 0, 1); PG8_SCHED; PG8_LDA(At, 0, 0); PG8_STAGE(PG8_SA(1, 1), a1 + hstep, voffA);
;             PG8_WAIT_V(8); PG8_WAIT_L(0); PG8_BAR; PG8_MMA(0, 0, At, B0); PG8_MMA(0, 1, At, B1); PG8_BAR; PG8_SCHED;
;             PG8_LDA(At, 0, 1); PG8_STAGE(PG8_SB(0, 0), b2, voffB); PG8_STAGE(PG8_SB(0, 1), b2 + hstep, voffB); PG8_STAGE(PG8_SA(0, 0), a2, voffA);
;             PG8_WAIT_V(8); PG8_WAIT_L(0); PG8_BAR; PG8_MMA(1, 0, At, B0); PG8_MMA(1, 1, At, B1); PG8_BAR; PG8_SCHED;
.LBB0_301:
	s_add_u32 s38, s36, 0xfff80080
	s_addc_u32 s39, s37, -1
	s_add_i32 s61, 0, 0x10000
	s_cmp_eq_u32 s60, 28
	s_cselect_b32 s41, s11, s39
	s_cselect_b32 s40, s13, s38
	s_cselect_b32 s39, s56, s59
	s_cselect_b32 s38, s57, s58
	s_add_i32 s64, 0, 0x14000
	v_add_u32_e32 v158, s61, v150
	v_add_u32_e32 v162, s64, v150
	ds_read_b128 v[142:145], v158
	ds_read_b128 v[146:149], v158 offset:1024
	ds_read_b128 v[154:157], v158 offset:2048
	ds_read_b128 v[158:161], v158 offset:3072
	ds_read_b128 v[174:177], v162
	ds_read_b128 v[178:181], v162 offset:1024
	ds_read_b128 v[204:207], v162 offset:2048
	ds_read_b128 v[208:211], v162 offset:3072
	s_add_i32 m0, s47, 0xc000
	ds_read_b128 v[212:215], v153
	ds_read_b128 v[216:219], v153 offset:1024
	ds_read_b128 v[220:223], v153 offset:2048
	ds_read_b128 v[224:227], v153 offset:3072
	ds_read_b128 v[228:231], v153 offset:4096
	ds_read_b128 v[232:235], v153 offset:5120
	ds_read_b128 v[236:239], v153 offset:6144
	ds_read_b128 v[240:243], v153 offset:7168
	global_load_lds_dwordx4 v138, s[36:37]
	s_nop 0
	s_waitcnt vmcnt(7)
	s_waitcnt lgkmcnt(0)
	s_barrier
	s_setprio 0
	s_waitcnt lgkmcnt(0)
	v_mfma_f32_16x16x32_bf16 v[128:131], v[142:145], v[212:215], v[128:131]
	v_mfma_f32_16x16x32_bf16 v[120:123], v[154:157], v[212:215], v[120:123]
	v_mfma_f32_16x16x32_bf16 v[112:115], v[142:145], v[220:223], v[112:115]
	s_add_i32 m0, s47, 0xe000
	v_mfma_f32_16x16x32_bf16 v[104:107], v[154:157], v[220:223], v[104:107]
	global_load_lds_dwordx4 v140, s[36:37]
	v_mfma_f32_16x16x32_bf16 v[96:99], v[142:145], v[228:231], v[96:99]
	v_mfma_f32_16x16x32_bf16 v[88:91], v[154:157], v[228:231], v[88:91]
	v_mfma_f32_16x16x32_bf16 v[80:83], v[142:145], v[236:239], v[80:83]
	v_mfma_f32_16x16x32_bf16 v[72:75], v[154:157], v[236:239], v[72:75]
	v_mfma_f32_16x16x32_bf16 v[128:131], v[146:149], v[216:219], v[128:131]
	v_mfma_f32_16x16x32_bf16 v[120:123], v[158:161], v[216:219], v[120:123]
	v_mfma_f32_16x16x32_bf16 v[112:115], v[146:149], v[224:227], v[112:115]
	v_mfma_f32_16x16x32_bf16 v[104:107], v[158:161], v[224:227], v[104:107]
	v_mfma_f32_16x16x32_bf16 v[96:99], v[146:149], v[232:235], v[96:99]
	v_mfma_f32_16x16x32_bf16 v[88:91], v[158:161], v[232:235], v[88:91]
	v_mfma_f32_16x16x32_bf16 v[80:83], v[146:149], v[240:243], v[80:83]
	v_mfma_f32_16x16x32_bf16 v[72:75], v[158:161], v[240:243], v[72:75]
	s_setprio 1
	s_setprio 0
	v_mfma_f32_16x16x32_bf16 v[124:127], v[174:177], v[212:215], v[124:127]
	v_mfma_f32_16x16x32_bf16 v[116:119], v[204:207], v[212:215], v[116:119]
	v_mfma_f32_16x16x32_bf16 v[108:111], v[174:177], v[220:223], v[108:111]
	v_mfma_f32_16x16x32_bf16 v[100:103], v[204:207], v[220:223], v[100:103]
	v_mfma_f32_16x16x32_bf16 v[92:95], v[174:177], v[228:231], v[92:95]
	v_mfma_f32_16x16x32_bf16 v[84:87], v[204:207], v[228:231], v[84:87]
	v_mfma_f32_16x16x32_bf16 v[76:79], v[174:177], v[236:239], v[76:79]
	v_mfma_f32_16x16x32_bf16 v[68:71], v[204:207], v[236:239], v[68:71]
	v_mfma_f32_16x16x32_bf16 v[124:127], v[178:181], v[216:219], v[124:127]
	v_mfma_f32_16x16x32_bf16 v[116:119], v[208:211], v[216:219], v[116:119]
	v_mfma_f32_16x16x32_bf16 v[108:111], v[178:181], v[224:227], v[108:111]
	v_mfma_f32_16x16x32_bf16 v[100:103], v[208:211], v[224:227], v[100:103]
	v_mfma_f32_16x16x32_bf16 v[92:95], v[178:181], v[232:235], v[92:95]
	v_mfma_f32_16x16x32_bf16 v[84:87], v[208:211], v[232:235], v[84:87]
	v_mfma_f32_16x16x32_bf16 v[76:79], v[178:181], v[240:243], v[76:79]
	v_mfma_f32_16x16x32_bf16 v[68:71], v[208:211], v[240:243], v[68:71]
	s_setprio 1
	s_barrier
	s_add_i32 s61, s61, s42
	s_mov_b32 m0, s61
	ds_read_b128 v[212:215], v153 offset:16384
	ds_read_b128 v[216:219], v153 offset:17408
	ds_read_b128 v[220:223], v153 offset:18432
	ds_read_b128 v[224:227], v153 offset:19456
	ds_read_b128 v[228:231], v153 offset:20480
	ds_read_b128 v[232:235], v153 offset:21504
	ds_read_b128 v[236:239], v153 offset:22528
	ds_read_b128 v[240:243], v153 offset:23552
	global_load_lds_dwordx4 v2, s[38:39]
	s_add_i32 m0, s61, 0x2000
	s_add_u32 s62, s38, 0x80000
	s_addc_u32 s63, s39, 0
	s_add_i32 s61, s64, s42
	global_load_lds_dwordx4 v132, s[38:39]
	s_mov_b32 m0, s61
	s_nop 0
	global_load_lds_dwordx4 v2, s[62:63]
	s_add_i32 m0, s61, 0x2000
	s_nop 0
	global_load_lds_dwordx4 v132, s[62:63]
	s_nop 0
	s_nop 0
	s_nop 0
	s_nop 0
	s_nop 0
	s_nop 0
	s_nop 0
	s_waitcnt vmcnt(6)
	s_waitcnt lgkmcnt(0)
	s_barrier
	s_setprio 0
	s_waitcnt lgkmcnt(0)
	v_mfma_f32_16x16x32_bf16 v[64:67], v[142:145], v[212:215], v[64:67]
	v_mfma_f32_16x16x32_bf16 v[56:59], v[154:157], v[212:215], v[56:59]
	v_mfma_f32_16x16x32_bf16 v[48:51], v[142:145], v[220:223], v[48:51]
	s_mov_b32 m0, s47
	v_mfma_f32_16x16x32_bf16 v[40:43], v[154:157], v[220:223], v[40:43]
	global_load_lds_dwordx4 v136, s[40:41]
	v_mfma_f32_16x16x32_bf16 v[32:35], v[142:145], v[228:231], v[32:35]
	v_mfma_f32_16x16x32_bf16 v[24:27], v[154:157], v[228:231], v[24:27]
	v_mfma_f32_16x16x32_bf16 v[16:19], v[142:145], v[236:239], v[16:19]
	v_mfma_f32_16x16x32_bf16 v[8:11], v[154:157], v[236:239], v[8:11]
	v_mfma_f32_16x16x32_bf16 v[64:67], v[146:149], v[216:219], v[64:67]
	v_mfma_f32_16x16x32_bf16 v[56:59], v[158:161], v[216:219], v[56:59]
	v_mfma_f32_16x16x32_bf16 v[48:51], v[146:149], v[224:227], v[48:51]
	s_mov_b32 m0, s48
	v_mfma_f32_16x16x32_bf16 v[40:43], v[158:161], v[224:227], v[40:43]
	global_load_lds_dwordx4 v134, s[40:41]
	v_mfma_f32_16x16x32_bf16 v[32:35], v[146:149], v[232:235], v[32:35]
	v_mfma_f32_16x16x32_bf16 v[24:27], v[158:161], v[232:235], v[24:27]
	v_mfma_f32_16x16x32_bf16 v[16:19], v[146:149], v[240:243], v[16:19]
	v_mfma_f32_16x16x32_bf16 v[8:11], v[158:161], v[240:243], v[8:11]
	s_setprio 1
	s_setprio 0
	v_mfma_f32_16x16x32_bf16 v[60:63], v[174:177], v[212:215], v[60:63]
	v_mfma_f32_16x16x32_bf16 v[52:55], v[204:207], v[212:215], v[52:55]
	v_mfma_f32_16x16x32_bf16 v[44:47], v[174:177], v[220:223], v[44:47]
	v_mfma_f32_16x16x32_bf16 v[36:39], v[204:207], v[220:223], v[36:39]
	v_mfma_f32_16x16x32_bf16 v[28:31], v[174:177], v[228:231], v[28:31]
	v_mfma_f32_16x16x32_bf16 v[20:23], v[204:207], v[228:231], v[20:23]
	v_mfma_f32_16x16x32_bf16 v[12:15], v[174:177], v[236:239], v[12:15]
	v_mfma_f32_16x16x32_bf16 v[4:7], v[204:207], v[236:239], v[4:7]
	v_mfma_f32_16x16x32_bf16 v[60:63], v[178:181], v[216:219], v[60:63]
	v_mfma_f32_16x16x32_bf16 v[52:55], v[208:211], v[216:219], v[52:55]
	v_mfma_f32_16x16x32_bf16 v[44:47], v[178:181], v[224:227], v[44:47]
	v_mfma_f32_16x16x32_bf16 v[36:39], v[208:211], v[224:227], v[36:39]
	v_mfma_f32_16x16x32_bf16 v[28:31], v[178:181], v[232:235], v[28:31]
	v_mfma_f32_16x16x32_bf16 v[20:23], v[208:211], v[232:235], v[20:23]
	v_mfma_f32_16x16x32_bf16 v[12:15], v[178:181], v[240:243], v[12:15]
	v_mfma_f32_16x16x32_bf16 v[4:7], v[208:211], v[240:243], v[4:7]
	s_setprio 1
	s_barrier
; #define PG8_STAGE(bufoff, gbase, voff) do { _Pragma("unroll") for (int _i = 0; _i < 2; ++_i) \
;         __builtin_amdgcn_global_load_lds((const unsigned*)((const char*)(gbase) + (voff)[_i]), (PG8_LAS unsigned*)(lds + (bufoff) + ldsw + _i * 8192), 16, 0, 0); } while (0)
; #define PG8_LDA(dst, b, h) do { _Pragma("unroll") for (int m = 0; m < 4; ++m) _Pragma("unroll") for (int k = 0; k < 2; ++k) dst[m][k] = *(const PG8_LAS bf16x8*)(lds + PG8_SA(b, h) + aoff + m * 2048 + k * 1024); } while (0)
; #define PG8_LDB(dst, b, h) do { _Pragma("unroll") for (int n = 0; n < 2; ++n) _Pragma("unroll") for (int k = 0; k < 2; ++k) dst[n][k] = *(const PG8_LAS bf16x8*)(lds + PG8_SB(b, h) + boff + n * 2048 + k * 1024); } while (0)
; #define PG8_MMA(ai, bj, At, Bt) do { __builtin_amdgcn_s_setprio(1); _Pragma("unroll") for (int m = 0; m < 4; ++m) _Pragma("unroll") for (int n = 0; n < 2; ++n) _Pragma("unroll") for (int k = 0; k < 2; ++k) \
;         acc[ai][bj][m][n] = __builtin_amdgcn_mfma_f32_16x16x32_bf16(Bt[n][k], At[m][k], acc[ai][bj][m][n], 0, 0, 0); __builtin_amdgcn_s_setprio(0); } while (0)
; #define PG8_WAIT_V(n) asm volatile("s_waitcnt vmcnt(" #n ")" ::: "memory")
; #define PG8_WAIT_L(n) asm volatile("s_waitcnt lgkmcnt(" #n ")" ::: "memory")
; #define PG8_BAR __builtin_amdgcn_s_barrier()
; #define PG8_SCHED __builtin_amdgcn_sched_barrier(0)
; template <class Epi, class Sched, bool ALIGN_EPI = false, bool SP2 = false>
; __device__ __forceinline__ void gemm_phase(PG8_LAS unsigned char* lds, const Gemm g, const Sched& S, const Epi& E) {
;     ...
;             PG8_LDB(B0, 1, 0); PG8_LDB(B1, 1, 1); PG8_SCHED; PG8_LDA(At, 1, 0); PG8_STAGE(PG8_SA(0, 1), a2 + hstep, voffA);
;             PG8_WAIT_V(8); PG8_WAIT_L(0); PG8_BAR; PG8_MMA(0, 0, At, B0); PG8_MMA(0, 1, At, B1); PG8_BAR; PG8_SCHED;
;             PG8_LDA(At, 1, 1); PG8_STAGE(PG8_SB(1, 0), b3, voffB); PG8_STAGE(PG8_SB(1, 1), b3 + hstep, voffB); PG8_STAGE(PG8_SA(1, 0), a3, voffA);
;             PG8_WAIT_V(8); PG8_WAIT_L(0); PG8_BAR; PG8_MMA(1, 0, At, B0); PG8_MMA(1, 1, At, B1); PG8_BAR; PG8_SCHED;
	s_add_i32 s61, 0, 0x18000
	s_add_i32 s62, 0, 0x1c000
	v_add_u32_e32 v158, s61, v150
	v_add_u32_e32 v164, s62, v150
	ds_read_b128 v[142:145], v158
	ds_read_b128 v[146:149], v158 offset:1024
	ds_read_b128 v[154:157], v158 offset:2048
	ds_read_b128 v[158:161], v158 offset:3072
	ds_read_b128 v[174:177], v164
	ds_read_b128 v[178:181], v164 offset:1024
	ds_read_b128 v[204:207], v164 offset:2048
	ds_read_b128 v[208:211], v164 offset:3072
	s_add_u32 s100, s40, 0x80
	s_addc_u32 s101, s41, 0
	s_add_u32 s40, s40, 0x80000
	s_addc_u32 s41, s41, 0
	s_mov_b32 m0, s49
	ds_read_b128 v[212:215], v153 offset:32768
	ds_read_b128 v[216:219], v153 offset:33792
	ds_read_b128 v[220:223], v153 offset:34816
	ds_read_b128 v[224:227], v153 offset:35840
	ds_read_b128 v[228:231], v153 offset:36864
	ds_read_b128 v[232:235], v153 offset:37888
	ds_read_b128 v[236:239], v153 offset:38912
	ds_read_b128 v[240:243], v153 offset:39936
	global_load_lds_dwordx4 v136, s[40:41]
	s_waitcnt vmcnt(7)
	s_waitcnt lgkmcnt(0)
	s_barrier
	s_setprio 0
	s_waitcnt lgkmcnt(0)
	v_mfma_f32_16x16x32_bf16 v[128:131], v[142:145], v[212:215], v[128:131]
	v_mfma_f32_16x16x32_bf16 v[120:123], v[154:157], v[212:215], v[120:123]
	v_mfma_f32_16x16x32_bf16 v[112:115], v[142:145], v[220:223], v[112:115]
	s_mov_b32 m0, s50
	v_mfma_f32_16x16x32_bf16 v[104:107], v[154:157], v[220:223], v[104:107]
	global_load_lds_dwordx4 v134, s[40:41]
	v_mfma_f32_16x16x32_bf16 v[96:99], v[142:145], v[228:231], v[96:99]
	v_mfma_f32_16x16x32_bf16 v[88:91], v[154:157], v[228:231], v[88:91]
	v_mfma_f32_16x16x32_bf16 v[80:83], v[142:145], v[236:239], v[80:83]
	v_mfma_f32_16x16x32_bf16 v[72:75], v[154:157], v[236:239], v[72:75]
	v_mfma_f32_16x16x32_bf16 v[128:131], v[146:149], v[216:219], v[128:131]
	v_mfma_f32_16x16x32_bf16 v[120:123], v[158:161], v[216:219], v[120:123]
	v_mfma_f32_16x16x32_bf16 v[112:115], v[146:149], v[224:227], v[112:115]
	v_mfma_f32_16x16x32_bf16 v[104:107], v[158:161], v[224:227], v[104:107]
	v_mfma_f32_16x16x32_bf16 v[96:99], v[146:149], v[232:235], v[96:99]
	v_mfma_f32_16x16x32_bf16 v[88:91], v[158:161], v[232:235], v[88:91]
	v_mfma_f32_16x16x32_bf16 v[80:83], v[146:149], v[240:243], v[80:83]
	v_mfma_f32_16x16x32_bf16 v[72:75], v[158:161], v[240:243], v[72:75]
	s_setprio 1
	s_setprio 0
	v_mfma_f32_16x16x32_bf16 v[124:127], v[174:177], v[212:215], v[124:127]
	v_mfma_f32_16x16x32_bf16 v[116:119], v[204:207], v[212:215], v[116:119]
	v_mfma_f32_16x16x32_bf16 v[108:111], v[174:177], v[220:223], v[108:111]
	v_mfma_f32_16x16x32_bf16 v[100:103], v[204:207], v[220:223], v[100:103]
	v_mfma_f32_16x16x32_bf16 v[92:95], v[174:177], v[228:231], v[92:95]
	v_mfma_f32_16x16x32_bf16 v[84:87], v[204:207], v[228:231], v[84:87]
	v_mfma_f32_16x16x32_bf16 v[76:79], v[174:177], v[236:239], v[76:79]
	v_mfma_f32_16x16x32_bf16 v[68:71], v[204:207], v[236:239], v[68:71]
	v_mfma_f32_16x16x32_bf16 v[124:127], v[178:181], v[216:219], v[124:127]
	v_mfma_f32_16x16x32_bf16 v[116:119], v[208:211], v[216:219], v[116:119]
	v_mfma_f32_16x16x32_bf16 v[108:111], v[178:181], v[224:227], v[108:111]
	v_mfma_f32_16x16x32_bf16 v[100:103], v[208:211], v[224:227], v[100:103]
	v_mfma_f32_16x16x32_bf16 v[92:95], v[178:181], v[232:235], v[92:95]
	v_mfma_f32_16x16x32_bf16 v[84:87], v[208:211], v[232:235], v[84:87]
	v_mfma_f32_16x16x32_bf16 v[76:79], v[178:181], v[240:243], v[76:79]
	v_mfma_f32_16x16x32_bf16 v[68:71], v[208:211], v[240:243], v[68:71]
	s_setprio 1
	s_barrier
	s_add_i32 s40, s61, s42
	s_add_i32 m0, s40, 0xffffff80
	ds_read_b128 v[212:215], v153 offset:49152
	ds_read_b128 v[216:219], v153 offset:50176
	ds_read_b128 v[220:223], v153 offset:51200
	ds_read_b128 v[224:227], v153 offset:52224
	ds_read_b128 v[228:231], v153 offset:53248
	ds_read_b128 v[232:235], v153 offset:54272
	ds_read_b128 v[236:239], v153 offset:55296
	ds_read_b128 v[240:243], v153 offset:56320
	global_load_lds_dwordx4 v2, s[38:39] offset:128
	s_add_i32 m0, s40, 0x1f80
	s_add_i32 s40, s62, s42
	global_load_lds_dwordx4 v132, s[38:39] offset:128
	s_add_u32 s38, s38, 0x80080
	s_addc_u32 s39, s39, 0
	s_mov_b32 m0, s40
	s_nop 0
	global_load_lds_dwordx4 v2, s[38:39]
	s_add_i32 m0, s40, 0x2000
	s_nop 0
	global_load_lds_dwordx4 v132, s[38:39]
	s_waitcnt vmcnt(6)
	s_waitcnt lgkmcnt(0)
	s_barrier
	s_setprio 0
	s_waitcnt lgkmcnt(0)
	v_mfma_f32_16x16x32_bf16 v[64:67], v[142:145], v[212:215], v[64:67]
	v_mfma_f32_16x16x32_bf16 v[56:59], v[154:157], v[212:215], v[56:59]
	v_mfma_f32_16x16x32_bf16 v[48:51], v[142:145], v[220:223], v[48:51]
	s_mov_b32 m0, s51
	v_mfma_f32_16x16x32_bf16 v[40:43], v[154:157], v[220:223], v[40:43]
	global_load_lds_dwordx4 v136, s[100:101]
	v_mfma_f32_16x16x32_bf16 v[32:35], v[142:145], v[228:231], v[32:35]
	v_mfma_f32_16x16x32_bf16 v[24:27], v[154:157], v[228:231], v[24:27]
	v_mfma_f32_16x16x32_bf16 v[16:19], v[142:145], v[236:239], v[16:19]
	v_mfma_f32_16x16x32_bf16 v[8:11], v[154:157], v[236:239], v[8:11]
	v_mfma_f32_16x16x32_bf16 v[64:67], v[146:149], v[216:219], v[64:67]
	v_mfma_f32_16x16x32_bf16 v[56:59], v[158:161], v[216:219], v[56:59]
	v_mfma_f32_16x16x32_bf16 v[48:51], v[146:149], v[224:227], v[48:51]
	s_mov_b32 m0, s53
	v_mfma_f32_16x16x32_bf16 v[40:43], v[158:161], v[224:227], v[40:43]
	global_load_lds_dwordx4 v134, s[100:101]
	v_mfma_f32_16x16x32_bf16 v[32:35], v[146:149], v[232:235], v[32:35]
	v_mfma_f32_16x16x32_bf16 v[24:27], v[158:161], v[232:235], v[24:27]
	v_mfma_f32_16x16x32_bf16 v[16:19], v[146:149], v[240:243], v[16:19]
	v_mfma_f32_16x16x32_bf16 v[8:11], v[158:161], v[240:243], v[8:11]
	s_setprio 1
	s_setprio 0
	v_mfma_f32_16x16x32_bf16 v[60:63], v[174:177], v[212:215], v[60:63]
	v_mfma_f32_16x16x32_bf16 v[52:55], v[204:207], v[212:215], v[52:55]
	v_mfma_f32_16x16x32_bf16 v[44:47], v[174:177], v[220:223], v[44:47]
	v_mfma_f32_16x16x32_bf16 v[36:39], v[204:207], v[220:223], v[36:39]
	v_mfma_f32_16x16x32_bf16 v[28:31], v[174:177], v[228:231], v[28:31]
	v_mfma_f32_16x16x32_bf16 v[20:23], v[204:207], v[228:231], v[20:23]
	v_mfma_f32_16x16x32_bf16 v[12:15], v[174:177], v[236:239], v[12:15]
	v_mfma_f32_16x16x32_bf16 v[4:7], v[204:207], v[236:239], v[4:7]
	v_mfma_f32_16x16x32_bf16 v[60:63], v[178:181], v[216:219], v[60:63]
	v_mfma_f32_16x16x32_bf16 v[52:55], v[208:211], v[216:219], v[52:55]
	v_mfma_f32_16x16x32_bf16 v[44:47], v[178:181], v[224:227], v[44:47]
	v_mfma_f32_16x16x32_bf16 v[36:39], v[208:211], v[224:227], v[36:39]
	v_mfma_f32_16x16x32_bf16 v[28:31], v[178:181], v[232:235], v[28:31]
	v_mfma_f32_16x16x32_bf16 v[20:23], v[208:211], v[232:235], v[20:23]
	v_mfma_f32_16x16x32_bf16 v[12:15], v[178:181], v[240:243], v[12:15]
	v_mfma_f32_16x16x32_bf16 v[4:7], v[208:211], v[240:243], v[4:7]
	s_setprio 1
	s_barrier
	s_add_i32 s60, s60, 2
	s_add_u32 s36, s36, 0x100
	s_addc_u32 s37, s37, 0
	s_add_u32 s58, s58, 0x100
	s_addc_u32 s59, s59, 0
	s_cmp_gt_u32 s60, 29
	s_cbranch_scc0 .LBB0_301
	s_and_b64 vcc, exec, s[8:9]
	s_cbranch_vccz .LBB0_304
	s_barrier

; #define PG8_STAGE(bufoff, gbase, voff) do { _Pragma("unroll") for (int _i = 0; _i < 2; ++_i) \
;         __builtin_amdgcn_global_load_lds((const unsigned*)((const char*)(gbase) + (voff)[_i]), (PG8_LAS unsigned*)(lds + (bufoff) + ldsw + _i * 8192), 16, 0, 0); } while (0)
; #define PG8_LDA(dst, b, h) do { _Pragma("unroll") for (int m = 0; m < 4; ++m) _Pragma("unroll") for (int k = 0; k < 2; ++k) dst[m][k] = *(const PG8_LAS bf16x8*)(lds + PG8_SA(b, h) + aoff + m * 2048 + k * 1024); } while (0)
; #define PG8_LDB(dst, b, h) do { _Pragma("unroll") for (int n = 0; n < 2; ++n) _Pragma("unroll") for (int k = 0; k < 2; ++k) dst[n][k] = *(const PG8_LAS bf16x8*)(lds + PG8_SB(b, h) + boff + n * 2048 + k * 1024); } while (0)
; #define PG8_MMA(ai, bj, At, Bt) do { __builtin_amdgcn_s_setprio(1); _Pragma("unroll") for (int m = 0; m < 4; ++m) _Pragma("unroll") for (int n = 0; n < 2; ++n) _Pragma("unroll") for (int k = 0; k < 2; ++k) \
;         acc[ai][bj][m][n] = __builtin_amdgcn_mfma_f32_16x16x32_bf16(Bt[n][k], At[m][k], acc[ai][bj][m][n], 0, 0, 0); __builtin_amdgcn_s_setprio(0); } while (0)
; #define PG8_WAIT_V(n) asm volatile("s_waitcnt vmcnt(" #n ")" ::: "memory")
; #define PG8_WAIT_L(n) asm volatile("s_waitcnt lgkmcnt(" #n ")" ::: "memory")
; #define PG8_BAR __builtin_amdgcn_s_barrier()
; #define PG8_SCHED __builtin_amdgcn_sched_barrier(0)
; template <class Epi, class Sched, bool ALIGN_EPI = false, bool SP2 = false>
; __device__ __forceinline__ void gemm_phase(PG8_LAS unsigned char* lds, const Gemm g, const Sched& S, const Epi& E) {
;     ...
;         for (int t = 0; t < nt; t += 2) {
;             const bool last = (t == nt - 2);
;             const char* a1 = cA + (size_t)(t + 1) * kstep;
;             const char* a2 = last ? nA : cA + (size_t)(t + 2) * kstep; const char* b2 = last ? nB : cB + (size_t)(t + 2) * kstep;
;             const char* a3 = a2 + kstep; const char* b3 = b2 + kstep;
;             if (last && has_next) S.a_ready(nxt);
;             if constexpr (SP2) {
;             PG8_LDB(B0, 0, 0); PG8_LDB(B1, 0, 1); PG8_SCHED; PG8_LDA(At, 0, 0); PG8_STAGE(PG8_SA(1, 1), a1 + hstep, voffA);
;             PG8_WAIT_V(8); PG8_WAIT_L(0); PG8_BAR; PG8_MMA(0, 0, At, B0); PG8_MMA(0, 1, At, B1); PG8_BAR; PG8_SCHED;
;             PG8_LDA(At, 0, 1); PG8_STAGE(PG8_SB(0, 0), b2, voffB); PG8_STAGE(PG8_SB(0, 1), b2 + hstep, voffB); PG8_STAGE(PG8_SA(0, 0), a2, voffA);
.LBB0_575:
	s_add_u32 s36, s34, 0x100
	s_addc_u32 s37, s35, 0
	s_add_i32 s64, 0, 0x10000
	s_cmpk_eq_i32 s63, 0x52
	s_cselect_b32 s41, s5, s37
	s_cselect_b32 s40, s4, s36
	v_add_u32_e32 v135, s64, v173
	s_cselect_b32 s39, s31, s62
	s_cselect_b32 s38, s30, s61
	s_add_i32 s65, 0, 0x14000
	ds_read_b128 v[142:145], v135
	ds_read_b128 v[146:149], v135 offset:1024
	ds_read_b128 v[150:153], v135 offset:2048
	ds_read_b128 v[154:157], v135 offset:3072
	v_add_u32_e32 v135, s65, v173
	ds_read_b128 v[158:161], v135
	ds_read_b128 v[174:177], v135 offset:1024
	ds_read_b128 v[180:183], v135 offset:2048
	ds_read_b128 v[204:207], v135 offset:3072
	v_lshl_add_u64 v[162:163], s[34:35], 0, v[138:139]
	s_add_i32 m0, s47, 0xc000
	ds_read_b128 v[208:211], v179
	ds_read_b128 v[212:215], v179 offset:1024
	ds_read_b128 v[216:219], v179 offset:2048
	ds_read_b128 v[220:223], v179 offset:3072
	ds_read_b128 v[224:227], v179 offset:4096
	ds_read_b128 v[228:231], v179 offset:5120
	ds_read_b128 v[232:235], v179 offset:6144
	ds_read_b128 v[236:239], v179 offset:7168
	global_load_lds_dwordx4 v[162:163], off
	v_lshl_add_u64 v[162:163], s[34:35], 0, v[140:141]
	s_nop 0
	s_waitcnt vmcnt(7)
	s_waitcnt lgkmcnt(0)
	s_barrier
	s_setprio 0
	s_waitcnt lgkmcnt(0)
	v_mfma_f32_16x16x32_bf16 v[128:131], v[142:145], v[208:211], v[128:131]
	v_mfma_f32_16x16x32_bf16 v[124:127], v[150:153], v[208:211], v[124:127]
	v_mfma_f32_16x16x32_bf16 v[112:115], v[142:145], v[216:219], v[112:115]
	s_add_i32 m0, s47, 0xe000
	v_mfma_f32_16x16x32_bf16 v[108:111], v[150:153], v[216:219], v[108:111]
	global_load_lds_dwordx4 v[162:163], off
	v_mfma_f32_16x16x32_bf16 v[96:99], v[142:145], v[224:227], v[96:99]
	v_mfma_f32_16x16x32_bf16 v[92:95], v[150:153], v[224:227], v[92:95]
	v_mfma_f32_16x16x32_bf16 v[80:83], v[142:145], v[232:235], v[80:83]
	v_mfma_f32_16x16x32_bf16 v[76:79], v[150:153], v[232:235], v[76:79]
	v_mfma_f32_16x16x32_bf16 v[128:131], v[146:149], v[212:215], v[128:131]
	v_mfma_f32_16x16x32_bf16 v[124:127], v[154:157], v[212:215], v[124:127]
	v_mfma_f32_16x16x32_bf16 v[112:115], v[146:149], v[220:223], v[112:115]
	v_mfma_f32_16x16x32_bf16 v[108:111], v[154:157], v[220:223], v[108:111]
	v_mfma_f32_16x16x32_bf16 v[96:99], v[146:149], v[228:231], v[96:99]
	v_mfma_f32_16x16x32_bf16 v[92:95], v[154:157], v[228:231], v[92:95]
	v_mfma_f32_16x16x32_bf16 v[80:83], v[146:149], v[236:239], v[80:83]
	v_mfma_f32_16x16x32_bf16 v[76:79], v[154:157], v[236:239], v[76:79]
	s_setprio 1
	s_setprio 0
	v_mfma_f32_16x16x32_bf16 v[120:123], v[158:161], v[208:211], v[120:123]
	v_mfma_f32_16x16x32_bf16 v[116:119], v[180:183], v[208:211], v[116:119]
	v_mfma_f32_16x16x32_bf16 v[104:107], v[158:161], v[216:219], v[104:107]
	v_mfma_f32_16x16x32_bf16 v[100:103], v[180:183], v[216:219], v[100:103]
	v_mfma_f32_16x16x32_bf16 v[88:91], v[158:161], v[224:227], v[88:91]
	v_mfma_f32_16x16x32_bf16 v[84:87], v[180:183], v[224:227], v[84:87]
	v_mfma_f32_16x16x32_bf16 v[72:75], v[158:161], v[232:235], v[72:75]
	v_mfma_f32_16x16x32_bf16 v[68:71], v[180:183], v[232:235], v[68:71]
	v_mfma_f32_16x16x32_bf16 v[120:123], v[174:177], v[212:215], v[120:123]
	v_mfma_f32_16x16x32_bf16 v[116:119], v[204:207], v[212:215], v[116:119]
	v_mfma_f32_16x16x32_bf16 v[104:107], v[174:177], v[220:223], v[104:107]
	v_mfma_f32_16x16x32_bf16 v[100:103], v[204:207], v[220:223], v[100:103]
	v_mfma_f32_16x16x32_bf16 v[88:91], v[174:177], v[228:231], v[88:91]
	v_mfma_f32_16x16x32_bf16 v[84:87], v[204:207], v[228:231], v[84:87]
	v_mfma_f32_16x16x32_bf16 v[72:75], v[174:177], v[236:239], v[72:75]
	v_mfma_f32_16x16x32_bf16 v[68:71], v[204:207], v[236:239], v[68:71]
	s_setprio 1
	s_barrier
	s_add_i32 s34, s64, s46
	s_mov_b32 m0, s34
	ds_read_b128 v[208:211], v179 offset:16384
	ds_read_b128 v[212:215], v179 offset:17408
	ds_read_b128 v[216:219], v179 offset:18432
	ds_read_b128 v[220:223], v179 offset:19456
	ds_read_b128 v[224:227], v179 offset:20480
	ds_read_b128 v[228:231], v179 offset:21504
	ds_read_b128 v[232:235], v179 offset:22528
	ds_read_b128 v[236:239], v179 offset:23552
	global_load_lds_dwordx4 v2, s[38:39]
	s_add_i32 m0, s34, 0x2000
	s_add_u32 s34, s38, 0x158000
	s_addc_u32 s35, s39, 0
	s_add_i32 s64, s65, s46
	global_load_lds_dwordx4 v132, s[38:39]
	s_mov_b32 m0, s64
	s_nop 0
	global_load_lds_dwordx4 v2, s[34:35]
	s_add_i32 m0, s64, 0x2000
	s_nop 0
	global_load_lds_dwordx4 v132, s[34:35]
	s_nop 0
	s_nop 0
	s_nop 0
	s_nop 0
	s_nop 0
	s_nop 0
	s_nop 0
	s_waitcnt vmcnt(6)
	s_waitcnt lgkmcnt(0)
	s_barrier
; #define PG8_STAGE(bufoff, gbase, voff) do { _Pragma("unroll") for (int _i = 0; _i < 2; ++_i) \
;         __builtin_amdgcn_global_load_lds((const unsigned*)((const char*)(gbase) + (voff)[_i]), (PG8_LAS unsigned*)(lds + (bufoff) + ldsw + _i * 8192), 16, 0, 0); } while (0)
; #define PG8_LDA(dst, b, h) do { _Pragma("unroll") for (int m = 0; m < 4; ++m) _Pragma("unroll") for (int k = 0; k < 2; ++k) dst[m][k] = *(const PG8_LAS bf16x8*)(lds + PG8_SA(b, h) + aoff + m * 2048 + k * 1024); } while (0)
; #define PG8_LDB(dst, b, h) do { _Pragma("unroll") for (int n = 0; n < 2; ++n) _Pragma("unroll") for (int k = 0; k < 2; ++k) dst[n][k] = *(const PG8_LAS bf16x8*)(lds + PG8_SB(b, h) + boff + n * 2048 + k * 1024); } while (0)
; #define PG8_MMA(ai, bj, At, Bt) do { __builtin_amdgcn_s_setprio(1); _Pragma("unroll") for (int m = 0; m < 4; ++m) _Pragma("unroll") for (int n = 0; n < 2; ++n) _Pragma("unroll") for (int k = 0; k < 2; ++k) \
;         acc[ai][bj][m][n] = __builtin_amdgcn_mfma_f32_16x16x32_bf16(Bt[n][k], At[m][k], acc[ai][bj][m][n], 0, 0, 0); __builtin_amdgcn_s_setprio(0); } while (0)
; #define PG8_WAIT_V(n) asm volatile("s_waitcnt vmcnt(" #n ")" ::: "memory")
; #define PG8_WAIT_L(n) asm volatile("s_waitcnt lgkmcnt(" #n ")" ::: "memory")
; #define PG8_BAR __builtin_amdgcn_s_barrier()
; #define PG8_SCHED __builtin_amdgcn_sched_barrier(0)
; template <class Epi, class Sched, bool ALIGN_EPI = false, bool SP2 = false>
; __device__ __forceinline__ void gemm_phase(PG8_LAS unsigned char* lds, const Gemm g, const Sched& S, const Epi& E) {
;     ...
;             PG8_LDA(At, 0, 1); PG8_STAGE(PG8_SB(0, 0), b2, voffB); PG8_STAGE(PG8_SB(0, 1), b2 + hstep, voffB); PG8_STAGE(PG8_SA(0, 0), a2, voffA);
;             PG8_WAIT_V(8); PG8_WAIT_L(0); PG8_BAR; PG8_MMA(1, 0, At, B0); PG8_MMA(1, 1, At, B1); PG8_BAR; PG8_SCHED;
;             PG8_LDB(B0, 1, 0); PG8_LDB(B1, 1, 1); PG8_SCHED; PG8_LDA(At, 1, 0); PG8_STAGE(PG8_SA(0, 1), a2 + hstep, voffA);
;             PG8_WAIT_V(8); PG8_WAIT_L(0); PG8_BAR; PG8_MMA(0, 0, At, B0); PG8_MMA(0, 1, At, B1); PG8_BAR; PG8_SCHED;
	s_setprio 0
	s_waitcnt lgkmcnt(0)
	v_mfma_f32_16x16x32_bf16 v[64:67], v[142:145], v[208:211], v[64:67]
	v_mfma_f32_16x16x32_bf16 v[60:63], v[150:153], v[208:211], v[60:63]
	v_mfma_f32_16x16x32_bf16 v[48:51], v[142:145], v[216:219], v[48:51]
	s_mov_b32 m0, s47
	v_mfma_f32_16x16x32_bf16 v[44:47], v[150:153], v[216:219], v[44:47]
	global_load_lds_dwordx4 v2, s[40:41]
	v_mfma_f32_16x16x32_bf16 v[32:35], v[142:145], v[224:227], v[32:35]
	v_mfma_f32_16x16x32_bf16 v[28:31], v[150:153], v[224:227], v[28:31]
	v_mfma_f32_16x16x32_bf16 v[16:19], v[142:145], v[232:235], v[16:19]
	v_mfma_f32_16x16x32_bf16 v[12:15], v[150:153], v[232:235], v[12:15]
	v_mfma_f32_16x16x32_bf16 v[64:67], v[146:149], v[212:215], v[64:67]
	v_mfma_f32_16x16x32_bf16 v[60:63], v[154:157], v[212:215], v[60:63]
	v_mfma_f32_16x16x32_bf16 v[48:51], v[146:149], v[220:223], v[48:51]
	s_mov_b32 m0, s48
	v_mfma_f32_16x16x32_bf16 v[44:47], v[154:157], v[220:223], v[44:47]
	global_load_lds_dwordx4 v132, s[40:41]
	v_mfma_f32_16x16x32_bf16 v[32:35], v[146:149], v[228:231], v[32:35]
	v_mfma_f32_16x16x32_bf16 v[28:31], v[154:157], v[228:231], v[28:31]
	v_mfma_f32_16x16x32_bf16 v[16:19], v[146:149], v[236:239], v[16:19]
	v_mfma_f32_16x16x32_bf16 v[12:15], v[154:157], v[236:239], v[12:15]
	s_setprio 1
	s_setprio 0
	v_mfma_f32_16x16x32_bf16 v[56:59], v[158:161], v[208:211], v[56:59]
	v_mfma_f32_16x16x32_bf16 v[52:55], v[180:183], v[208:211], v[52:55]
	v_mfma_f32_16x16x32_bf16 v[40:43], v[158:161], v[216:219], v[40:43]
	v_mfma_f32_16x16x32_bf16 v[36:39], v[180:183], v[216:219], v[36:39]
	v_mfma_f32_16x16x32_bf16 v[24:27], v[158:161], v[224:227], v[24:27]
	v_mfma_f32_16x16x32_bf16 v[20:23], v[180:183], v[224:227], v[20:23]
	v_mfma_f32_16x16x32_bf16 v[8:11], v[158:161], v[232:235], v[8:11]
	v_mfma_f32_16x16x32_bf16 v[4:7], v[180:183], v[232:235], v[4:7]
	v_mfma_f32_16x16x32_bf16 v[56:59], v[174:177], v[212:215], v[56:59]
	v_mfma_f32_16x16x32_bf16 v[52:55], v[204:207], v[212:215], v[52:55]
	v_mfma_f32_16x16x32_bf16 v[40:43], v[174:177], v[220:223], v[40:43]
	v_mfma_f32_16x16x32_bf16 v[36:39], v[204:207], v[220:223], v[36:39]
	v_mfma_f32_16x16x32_bf16 v[24:27], v[174:177], v[228:231], v[24:27]
	v_mfma_f32_16x16x32_bf16 v[20:23], v[204:207], v[228:231], v[20:23]
	v_mfma_f32_16x16x32_bf16 v[8:11], v[174:177], v[236:239], v[8:11]
	v_mfma_f32_16x16x32_bf16 v[4:7], v[204:207], v[236:239], v[4:7]
	s_setprio 1
	s_barrier
	s_add_i32 s64, 0, 0x18000
	v_add_u32_e32 v135, s64, v173
	s_add_i32 s65, 0, 0x1c000
	ds_read_b128 v[142:145], v135
	ds_read_b128 v[146:149], v135 offset:1024
	ds_read_b128 v[150:153], v135 offset:2048
	ds_read_b128 v[154:157], v135 offset:3072
	v_add_u32_e32 v135, s65, v173
	ds_read_b128 v[158:161], v135
	ds_read_b128 v[174:177], v135 offset:1024
	ds_read_b128 v[180:183], v135 offset:2048
	ds_read_b128 v[204:207], v135 offset:3072
	s_add_u32 s34, s40, 0x158000
	s_addc_u32 s35, s41, 0
	s_mov_b32 m0, s49
	ds_read_b128 v[208:211], v179 offset:32768
	ds_read_b128 v[212:215], v179 offset:33792
	ds_read_b128 v[216:219], v179 offset:34816
	ds_read_b128 v[220:223], v179 offset:35840
	ds_read_b128 v[224:227], v179 offset:36864
	ds_read_b128 v[228:231], v179 offset:37888
	ds_read_b128 v[232:235], v179 offset:38912
	ds_read_b128 v[236:239], v179 offset:39936
	global_load_lds_dwordx4 v2, s[34:35]
	s_waitcnt vmcnt(7)
	s_waitcnt lgkmcnt(0)
	s_barrier
	s_setprio 0
	s_waitcnt lgkmcnt(0)
	v_mfma_f32_16x16x32_bf16 v[128:131], v[142:145], v[208:211], v[128:131]
	v_mfma_f32_16x16x32_bf16 v[124:127], v[150:153], v[208:211], v[124:127]
	v_mfma_f32_16x16x32_bf16 v[112:115], v[142:145], v[216:219], v[112:115]
	s_mov_b32 m0, s50
	v_mfma_f32_16x16x32_bf16 v[108:111], v[150:153], v[216:219], v[108:111]
	global_load_lds_dwordx4 v132, s[34:35]
	v_mfma_f32_16x16x32_bf16 v[96:99], v[142:145], v[224:227], v[96:99]
	v_mfma_f32_16x16x32_bf16 v[92:95], v[150:153], v[224:227], v[92:95]
	v_mfma_f32_16x16x32_bf16 v[80:83], v[142:145], v[232:235], v[80:83]
	v_mfma_f32_16x16x32_bf16 v[76:79], v[150:153], v[232:235], v[76:79]
	v_mfma_f32_16x16x32_bf16 v[128:131], v[146:149], v[212:215], v[128:131]
	v_mfma_f32_16x16x32_bf16 v[124:127], v[154:157], v[212:215], v[124:127]
	v_mfma_f32_16x16x32_bf16 v[112:115], v[146:149], v[220:223], v[112:115]
	v_mfma_f32_16x16x32_bf16 v[108:111], v[154:157], v[220:223], v[108:111]
	v_mfma_f32_16x16x32_bf16 v[96:99], v[146:149], v[228:231], v[96:99]
	v_mfma_f32_16x16x32_bf16 v[92:95], v[154:157], v[228:231], v[92:95]
	v_mfma_f32_16x16x32_bf16 v[80:83], v[146:149], v[236:239], v[80:83]
	v_mfma_f32_16x16x32_bf16 v[76:79], v[154:157], v[236:239], v[76:79]
	s_setprio 1
	s_setprio 0
	v_mfma_f32_16x16x32_bf16 v[120:123], v[158:161], v[208:211], v[120:123]
	v_mfma_f32_16x16x32_bf16 v[116:119], v[180:183], v[208:211], v[116:119]
	v_mfma_f32_16x16x32_bf16 v[104:107], v[158:161], v[216:219], v[104:107]
	v_mfma_f32_16x16x32_bf16 v[100:103], v[180:183], v[216:219], v[100:103]
	v_mfma_f32_16x16x32_bf16 v[88:91], v[158:161], v[224:227], v[88:91]
	v_mfma_f32_16x16x32_bf16 v[84:87], v[180:183], v[224:227], v[84:87]
	v_mfma_f32_16x16x32_bf16 v[72:75], v[158:161], v[232:235], v[72:75]
	v_mfma_f32_16x16x32_bf16 v[68:71], v[180:183], v[232:235], v[68:71]
	v_mfma_f32_16x16x32_bf16 v[120:123], v[174:177], v[212:215], v[120:123]
	v_mfma_f32_16x16x32_bf16 v[116:119], v[204:207], v[212:215], v[116:119]
	v_mfma_f32_16x16x32_bf16 v[104:107], v[174:177], v[220:223], v[104:107]
	v_mfma_f32_16x16x32_bf16 v[100:103], v[204:207], v[220:223], v[100:103]
	v_mfma_f32_16x16x32_bf16 v[88:91], v[174:177], v[228:231], v[88:91]
	v_mfma_f32_16x16x32_bf16 v[84:87], v[204:207], v[228:231], v[84:87]
	v_mfma_f32_16x16x32_bf16 v[72:75], v[174:177], v[236:239], v[72:75]
	v_mfma_f32_16x16x32_bf16 v[68:71], v[204:207], v[236:239], v[68:71]
	s_setprio 1
	s_barrier
; #define PG8_STAGE(bufoff, gbase, voff) do { _Pragma("unroll") for (int _i = 0; _i < 2; ++_i) \
;         __builtin_amdgcn_global_load_lds((const unsigned*)((const char*)(gbase) + (voff)[_i]), (PG8_LAS unsigned*)(lds + (bufoff) + ldsw + _i * 8192), 16, 0, 0); } while (0)
; #define PG8_LDA(dst, b, h) do { _Pragma("unroll") for (int m = 0; m < 4; ++m) _Pragma("unroll") for (int k = 0; k < 2; ++k) dst[m][k] = *(const PG8_LAS bf16x8*)(lds + PG8_SA(b, h) + aoff + m * 2048 + k * 1024); } while (0)
; #define PG8_MMA(ai, bj, At, Bt) do { __builtin_amdgcn_s_setprio(1); _Pragma("unroll") for (int m = 0; m < 4; ++m) _Pragma("unroll") for (int n = 0; n < 2; ++n) _Pragma("unroll") for (int k = 0; k < 2; ++k) \
;         acc[ai][bj][m][n] = __builtin_amdgcn_mfma_f32_16x16x32_bf16(Bt[n][k], At[m][k], acc[ai][bj][m][n], 0, 0, 0); __builtin_amdgcn_s_setprio(0); } while (0)
; #define PG8_WAIT_V(n) asm volatile("s_waitcnt vmcnt(" #n ")" ::: "memory")
; #define PG8_WAIT_L(n) asm volatile("s_waitcnt lgkmcnt(" #n ")" ::: "memory")
; #define PG8_BAR __builtin_amdgcn_s_barrier()
; #define PG8_SCHED __builtin_amdgcn_sched_barrier(0)
; template <class Epi, class Sched, bool ALIGN_EPI = false, bool SP2 = false>
; __device__ __forceinline__ void gemm_phase(PG8_LAS unsigned char* lds, const Gemm g, const Sched& S, const Epi& E) {
;     ...
;             PG8_LDA(At, 1, 1); PG8_STAGE(PG8_SB(1, 0), b3, voffB); PG8_STAGE(PG8_SB(1, 1), b3 + hstep, voffB); PG8_STAGE(PG8_SA(1, 0), a3, voffA);
;             PG8_WAIT_V(8); PG8_WAIT_L(0); PG8_BAR; PG8_MMA(1, 0, At, B0); PG8_MMA(1, 1, At, B1); PG8_BAR; PG8_SCHED;
	s_add_i32 s34, s64, s46
	s_add_i32 m0, s34, 0xffffff80
	ds_read_b128 v[208:211], v179 offset:49152
	ds_read_b128 v[212:215], v179 offset:50176
	ds_read_b128 v[216:219], v179 offset:51200
	ds_read_b128 v[220:223], v179 offset:52224
	ds_read_b128 v[224:227], v179 offset:53248
	ds_read_b128 v[228:231], v179 offset:54272
	ds_read_b128 v[232:235], v179 offset:55296
	ds_read_b128 v[236:239], v179 offset:56320
	global_load_lds_dwordx4 v2, s[38:39] offset:128
	s_add_i32 m0, s34, 0x1f80
	s_add_u32 s34, s38, 0x158080
	s_addc_u32 s35, s39, 0
	global_load_lds_dwordx4 v132, s[38:39] offset:128
	s_add_i32 s38, s65, s46
	s_mov_b32 m0, s38
	s_nop 0
	global_load_lds_dwordx4 v2, s[34:35]
	s_add_i32 m0, s38, 0x2000
	s_nop 0
	global_load_lds_dwordx4 v132, s[34:35]
	s_waitcnt vmcnt(6)
	s_waitcnt lgkmcnt(0)
	s_barrier
	s_setprio 0
	s_waitcnt lgkmcnt(0)
	v_mfma_f32_16x16x32_bf16 v[64:67], v[142:145], v[208:211], v[64:67]
	v_mfma_f32_16x16x32_bf16 v[60:63], v[150:153], v[208:211], v[60:63]
	v_mfma_f32_16x16x32_bf16 v[48:51], v[142:145], v[216:219], v[48:51]
	s_add_i32 m0, s53, 0xffffff80
	v_mfma_f32_16x16x32_bf16 v[44:47], v[150:153], v[216:219], v[44:47]
	global_load_lds_dwordx4 v2, s[40:41] offset:128
	v_mfma_f32_16x16x32_bf16 v[32:35], v[142:145], v[224:227], v[32:35]
	v_mfma_f32_16x16x32_bf16 v[28:31], v[150:153], v[224:227], v[28:31]
	v_mfma_f32_16x16x32_bf16 v[16:19], v[142:145], v[232:235], v[16:19]
	v_mfma_f32_16x16x32_bf16 v[12:15], v[150:153], v[232:235], v[12:15]
	v_mfma_f32_16x16x32_bf16 v[64:67], v[146:149], v[212:215], v[64:67]
	v_mfma_f32_16x16x32_bf16 v[60:63], v[154:157], v[212:215], v[60:63]
	v_mfma_f32_16x16x32_bf16 v[48:51], v[146:149], v[220:223], v[48:51]
	s_add_i32 m0, s54, 0xffffff80
	v_mfma_f32_16x16x32_bf16 v[44:47], v[154:157], v[220:223], v[44:47]
	global_load_lds_dwordx4 v132, s[40:41] offset:128
	v_mfma_f32_16x16x32_bf16 v[32:35], v[146:149], v[228:231], v[32:35]
	v_mfma_f32_16x16x32_bf16 v[28:31], v[154:157], v[228:231], v[28:31]
	v_mfma_f32_16x16x32_bf16 v[16:19], v[146:149], v[236:239], v[16:19]
	v_mfma_f32_16x16x32_bf16 v[12:15], v[154:157], v[236:239], v[12:15]
	s_setprio 1
	s_setprio 0
	v_mfma_f32_16x16x32_bf16 v[56:59], v[158:161], v[208:211], v[56:59]
	v_mfma_f32_16x16x32_bf16 v[52:55], v[180:183], v[208:211], v[52:55]
	v_mfma_f32_16x16x32_bf16 v[40:43], v[158:161], v[216:219], v[40:43]
	v_mfma_f32_16x16x32_bf16 v[36:39], v[180:183], v[216:219], v[36:39]
	v_mfma_f32_16x16x32_bf16 v[24:27], v[158:161], v[224:227], v[24:27]
	v_mfma_f32_16x16x32_bf16 v[20:23], v[180:183], v[224:227], v[20:23]
	v_mfma_f32_16x16x32_bf16 v[8:11], v[158:161], v[232:235], v[8:11]
	v_mfma_f32_16x16x32_bf16 v[4:7], v[180:183], v[232:235], v[4:7]
	v_mfma_f32_16x16x32_bf16 v[56:59], v[174:177], v[212:215], v[56:59]
	v_mfma_f32_16x16x32_bf16 v[52:55], v[204:207], v[212:215], v[52:55]
	v_mfma_f32_16x16x32_bf16 v[40:43], v[174:177], v[220:223], v[40:43]
	v_mfma_f32_16x16x32_bf16 v[36:39], v[204:207], v[220:223], v[36:39]
	v_mfma_f32_16x16x32_bf16 v[24:27], v[174:177], v[228:231], v[24:27]
	v_mfma_f32_16x16x32_bf16 v[20:23], v[204:207], v[228:231], v[20:23]
	v_mfma_f32_16x16x32_bf16 v[8:11], v[174:177], v[236:239], v[8:11]
	v_mfma_f32_16x16x32_bf16 v[4:7], v[204:207], v[236:239], v[4:7]
	s_setprio 1
	s_barrier
	s_add_i32 s63, s63, 2
	s_add_u32 s61, s61, 0x100
	s_addc_u32 s62, s62, 0
	s_cmpk_gt_u32 s63, 0x53
	s_mov_b64 s[34:35], s[36:37]
	s_cbranch_scc0 .LBB0_575
	s_and_b64 vcc, exec, s[28:29]
	s_cbranch_vccz .LBB0_578
	s_barrier

; #define PG8_STAGE(bufoff, gbase, voff) do { _Pragma("unroll") for (int _i = 0; _i < 2; ++_i) \
;         __builtin_amdgcn_global_load_lds((const unsigned*)((const char*)(gbase) + (voff)[_i]), (PG8_LAS unsigned*)(lds + (bufoff) + ldsw + _i * 8192), 16, 0, 0); } while (0)
; #define PG8_LDA(dst, b, h) do { _Pragma("unroll") for (int m = 0; m < 4; ++m) _Pragma("unroll") for (int k = 0; k < 2; ++k) dst[m][k] = *(const PG8_LAS bf16x8*)(lds + PG8_SA(b, h) + aoff + m * 2048 + k * 1024); } while (0)
; #define PG8_LDB(dst, b, h) do { _Pragma("unroll") for (int n = 0; n < 2; ++n) _Pragma("unroll") for (int k = 0; k < 2; ++k) dst[n][k] = *(const PG8_LAS bf16x8*)(lds + PG8_SB(b, h) + boff + n * 2048 + k * 1024); } while (0)
; #define PG8_MMA(ai, bj, At, Bt) do { __builtin_amdgcn_s_setprio(1); _Pragma("unroll") for (int m = 0; m < 4; ++m) _Pragma("unroll") for (int n = 0; n < 2; ++n) _Pragma("unroll") for (int k = 0; k < 2; ++k) \
;         acc[ai][bj][m][n] = __builtin_amdgcn_mfma_f32_16x16x32_bf16(Bt[n][k], At[m][k], acc[ai][bj][m][n], 0, 0, 0); __builtin_amdgcn_s_setprio(0); } while (0)
; #define PG8_WAIT_V(n) asm volatile("s_waitcnt vmcnt(" #n ")" ::: "memory")
; #define PG8_BAR __builtin_amdgcn_s_barrier()
; template <class Epi, class Sched, bool ALIGN_EPI = false, bool SP2 = false>
; __device__ __forceinline__ void gemm_phase(PG8_LAS unsigned char* lds, const Gemm g, const Sched& S, const Epi& E) {
;     ...
;         for (int t = 0; t < nt; t += 2) {
;             const bool last = (t == nt - 2);
;             const char* a1 = cA + (size_t)(t + 1) * kstep;
;             const char* a2 = last ? nA : cA + (size_t)(t + 2) * kstep; const char* b2 = last ? nB : cB + (size_t)(t + 2) * kstep;
;             const char* a3 = a2 + kstep; const char* b3 = b2 + kstep;
;             if (last && has_next) S.a_ready(nxt);
;             if constexpr (SP2) {
;             PG8_LDB(B0, 0, 0); PG8_LDB(B1, 0, 1); PG8_SCHED; PG8_LDA(At, 0, 0); PG8_STAGE(PG8_SA(1, 1), a1 + hstep, voffA);
;             PG8_WAIT_V(8); PG8_WAIT_L(0); PG8_BAR; PG8_MMA(0, 0, At, B0); PG8_MMA(0, 1, At, B1); PG8_BAR; PG8_SCHED;
;             PG8_LDA(At, 0, 1); PG8_STAGE(PG8_SB(0, 0), b2, voffB); PG8_STAGE(PG8_SB(0, 1), b2 + hstep, voffB); PG8_STAGE(PG8_SA(0, 0), a2, voffA);
;             PG8_WAIT_V(8); PG8_WAIT_L(0); PG8_BAR; PG8_MMA(1, 0, At, B0); PG8_MMA(1, 1, At, B1); PG8_BAR; PG8_SCHED;
.LBB0_674:
	s_add_u32 s42, s40, 0xfff80080
	s_addc_u32 s43, s41, -1
	s_add_i32 s64, 0, 0x10000
	s_cmp_eq_u32 s63, 28
	s_cselect_b32 s45, s5, s43
	s_cselect_b32 s44, s4, s42
	s_cselect_b32 s43, s37, s62
	s_cselect_b32 s42, s36, s35
	s_add_i32 s66, 0, 0x14000
	v_add_u32_e32 v144, s64, v173
	v_add_u32_e32 v162, s66, v173
	ds_read_b128 v[132:135], v144
	ds_read_b128 v[136:139], v144 offset:1024
	ds_read_b128 v[140:143], v144 offset:2048
	ds_read_b128 v[144:147], v144 offset:3072
	ds_read_b128 v[158:161], v162
	ds_read_b128 v[174:177], v162 offset:1024
	ds_read_b128 v[206:209], v162 offset:2048
	ds_read_b128 v[210:213], v162 offset:3072
	s_add_i32 m0, s39, 0xc000
	ds_read_b128 v[214:217], v204
	ds_read_b128 v[218:221], v204 offset:1024
	ds_read_b128 v[222:225], v204 offset:2048
	ds_read_b128 v[226:229], v204 offset:3072
	ds_read_b128 v[230:233], v204 offset:4096
	ds_read_b128 v[234:237], v204 offset:5120
	ds_read_b128 v[238:241], v204 offset:6144
	ds_read_b128 v[242:245], v204 offset:7168
	global_load_lds_dwordx4 v154, s[40:41]
	s_nop 0
	s_waitcnt vmcnt(7)
	s_waitcnt lgkmcnt(0)
	s_barrier
	s_setprio 0
	s_waitcnt lgkmcnt(0)
	v_mfma_f32_16x16x32_bf16 v[128:131], v[132:135], v[214:217], v[128:131]
	v_mfma_f32_16x16x32_bf16 v[124:127], v[140:143], v[214:217], v[124:127]
	v_mfma_f32_16x16x32_bf16 v[116:119], v[132:135], v[222:225], v[116:119]
	s_add_i32 m0, s39, 0xe000
	v_mfma_f32_16x16x32_bf16 v[108:111], v[140:143], v[222:225], v[108:111]
	global_load_lds_dwordx4 v156, s[40:41]
	v_mfma_f32_16x16x32_bf16 v[100:103], v[132:135], v[230:233], v[100:103]
	v_mfma_f32_16x16x32_bf16 v[92:95], v[140:143], v[230:233], v[92:95]
	v_mfma_f32_16x16x32_bf16 v[84:87], v[132:135], v[238:241], v[84:87]
	v_mfma_f32_16x16x32_bf16 v[76:79], v[140:143], v[238:241], v[76:79]
	v_mfma_f32_16x16x32_bf16 v[128:131], v[136:139], v[218:221], v[128:131]
	v_mfma_f32_16x16x32_bf16 v[124:127], v[144:147], v[218:221], v[124:127]
	v_mfma_f32_16x16x32_bf16 v[116:119], v[136:139], v[226:229], v[116:119]
	v_mfma_f32_16x16x32_bf16 v[108:111], v[144:147], v[226:229], v[108:111]
	v_mfma_f32_16x16x32_bf16 v[100:103], v[136:139], v[234:237], v[100:103]
	v_mfma_f32_16x16x32_bf16 v[92:95], v[144:147], v[234:237], v[92:95]
	v_mfma_f32_16x16x32_bf16 v[84:87], v[136:139], v[242:245], v[84:87]
	v_mfma_f32_16x16x32_bf16 v[76:79], v[144:147], v[242:245], v[76:79]
	s_setprio 1
	s_setprio 0
	v_mfma_f32_16x16x32_bf16 v[120:123], v[158:161], v[214:217], v[120:123]
	v_mfma_f32_16x16x32_bf16 v[112:115], v[206:209], v[214:217], v[112:115]
	v_mfma_f32_16x16x32_bf16 v[104:107], v[158:161], v[222:225], v[104:107]
	v_mfma_f32_16x16x32_bf16 v[96:99], v[206:209], v[222:225], v[96:99]
	v_mfma_f32_16x16x32_bf16 v[88:91], v[158:161], v[230:233], v[88:91]
	v_mfma_f32_16x16x32_bf16 v[80:83], v[206:209], v[230:233], v[80:83]
	v_mfma_f32_16x16x32_bf16 v[72:75], v[158:161], v[238:241], v[72:75]
	v_mfma_f32_16x16x32_bf16 v[68:71], v[206:209], v[238:241], v[68:71]
	v_mfma_f32_16x16x32_bf16 v[120:123], v[174:177], v[218:221], v[120:123]
	v_mfma_f32_16x16x32_bf16 v[112:115], v[210:213], v[218:221], v[112:115]
	v_mfma_f32_16x16x32_bf16 v[104:107], v[174:177], v[226:229], v[104:107]
	v_mfma_f32_16x16x32_bf16 v[96:99], v[210:213], v[226:229], v[96:99]
	v_mfma_f32_16x16x32_bf16 v[88:91], v[174:177], v[234:237], v[88:91]
	v_mfma_f32_16x16x32_bf16 v[80:83], v[210:213], v[234:237], v[80:83]
	v_mfma_f32_16x16x32_bf16 v[72:75], v[174:177], v[242:245], v[72:75]
	v_mfma_f32_16x16x32_bf16 v[68:71], v[210:213], v[242:245], v[68:71]
	s_setprio 1
	s_barrier
	s_add_i32 s64, s64, s46
	s_mov_b32 m0, s64
	ds_read_b128 v[214:217], v204 offset:16384
	ds_read_b128 v[218:221], v204 offset:17408
	ds_read_b128 v[222:225], v204 offset:18432
	ds_read_b128 v[226:229], v204 offset:19456
	ds_read_b128 v[230:233], v204 offset:20480
	ds_read_b128 v[234:237], v204 offset:21504
	ds_read_b128 v[238:241], v204 offset:22528
	ds_read_b128 v[242:245], v204 offset:23552
	global_load_lds_dwordx4 v2, s[42:43]
	s_add_i32 m0, s64, 0x2000
	s_add_u32 s64, s42, 0x80000
	s_addc_u32 s65, s43, 0
	s_add_i32 s66, s66, s46
	global_load_lds_dwordx4 v148, s[42:43]
	s_mov_b32 m0, s66
	s_nop 0
	global_load_lds_dwordx4 v2, s[64:65]
	s_add_i32 m0, s66, 0x2000
	s_nop 0
	global_load_lds_dwordx4 v148, s[64:65]
	s_nop 0
	s_nop 0
	s_nop 0
	s_nop 0
	s_nop 0
	s_nop 0
	s_nop 0
	s_waitcnt vmcnt(6)
	s_waitcnt lgkmcnt(0)
	s_barrier
	s_setprio 0
	s_waitcnt lgkmcnt(0)
	v_mfma_f32_16x16x32_bf16 v[64:67], v[132:135], v[214:217], v[64:67]
	v_mfma_f32_16x16x32_bf16 v[60:63], v[140:143], v[214:217], v[60:63]
	v_mfma_f32_16x16x32_bf16 v[52:55], v[132:135], v[222:225], v[52:55]
	s_mov_b32 m0, s39
	v_mfma_f32_16x16x32_bf16 v[44:47], v[140:143], v[222:225], v[44:47]
	global_load_lds_dwordx4 v152, s[44:45]
	v_mfma_f32_16x16x32_bf16 v[36:39], v[132:135], v[230:233], v[36:39]
	v_mfma_f32_16x16x32_bf16 v[28:31], v[140:143], v[230:233], v[28:31]
	v_mfma_f32_16x16x32_bf16 v[20:23], v[132:135], v[238:241], v[20:23]
	v_mfma_f32_16x16x32_bf16 v[12:15], v[140:143], v[238:241], v[12:15]
	v_mfma_f32_16x16x32_bf16 v[64:67], v[136:139], v[218:221], v[64:67]
	v_mfma_f32_16x16x32_bf16 v[60:63], v[144:147], v[218:221], v[60:63]
	v_mfma_f32_16x16x32_bf16 v[52:55], v[136:139], v[226:229], v[52:55]
	s_mov_b32 m0, s51
	v_mfma_f32_16x16x32_bf16 v[44:47], v[144:147], v[226:229], v[44:47]
	global_load_lds_dwordx4 v150, s[44:45]
	v_mfma_f32_16x16x32_bf16 v[36:39], v[136:139], v[234:237], v[36:39]
	v_mfma_f32_16x16x32_bf16 v[28:31], v[144:147], v[234:237], v[28:31]
	v_mfma_f32_16x16x32_bf16 v[20:23], v[136:139], v[242:245], v[20:23]
	v_mfma_f32_16x16x32_bf16 v[12:15], v[144:147], v[242:245], v[12:15]
	s_setprio 1
	s_setprio 0
	v_mfma_f32_16x16x32_bf16 v[56:59], v[158:161], v[214:217], v[56:59]
	v_mfma_f32_16x16x32_bf16 v[48:51], v[206:209], v[214:217], v[48:51]
	v_mfma_f32_16x16x32_bf16 v[40:43], v[158:161], v[222:225], v[40:43]
	v_mfma_f32_16x16x32_bf16 v[32:35], v[206:209], v[222:225], v[32:35]
	v_mfma_f32_16x16x32_bf16 v[24:27], v[158:161], v[230:233], v[24:27]
	v_mfma_f32_16x16x32_bf16 v[16:19], v[206:209], v[230:233], v[16:19]
	v_mfma_f32_16x16x32_bf16 v[8:11], v[158:161], v[238:241], v[8:11]
	v_mfma_f32_16x16x32_bf16 v[4:7], v[206:209], v[238:241], v[4:7]
	v_mfma_f32_16x16x32_bf16 v[56:59], v[174:177], v[218:221], v[56:59]
	v_mfma_f32_16x16x32_bf16 v[48:51], v[210:213], v[218:221], v[48:51]
	v_mfma_f32_16x16x32_bf16 v[40:43], v[174:177], v[226:229], v[40:43]
	v_mfma_f32_16x16x32_bf16 v[32:35], v[210:213], v[226:229], v[32:35]
	v_mfma_f32_16x16x32_bf16 v[24:27], v[174:177], v[234:237], v[24:27]
	v_mfma_f32_16x16x32_bf16 v[16:19], v[210:213], v[234:237], v[16:19]
	v_mfma_f32_16x16x32_bf16 v[8:11], v[174:177], v[242:245], v[8:11]
	v_mfma_f32_16x16x32_bf16 v[4:7], v[210:213], v[242:245], v[4:7]
	s_setprio 1
	s_barrier
; #define PG8_STAGE(bufoff, gbase, voff) do { _Pragma("unroll") for (int _i = 0; _i < 2; ++_i) \
;         __builtin_amdgcn_global_load_lds((const unsigned*)((const char*)(gbase) + (voff)[_i]), (PG8_LAS unsigned*)(lds + (bufoff) + ldsw + _i * 8192), 16, 0, 0); } while (0)
; #define PG8_LDA(dst, b, h) do { _Pragma("unroll") for (int m = 0; m < 4; ++m) _Pragma("unroll") for (int k = 0; k < 2; ++k) dst[m][k] = *(const PG8_LAS bf16x8*)(lds + PG8_SA(b, h) + aoff + m * 2048 + k * 1024); } while (0)
; #define PG8_LDB(dst, b, h) do { _Pragma("unroll") for (int n = 0; n < 2; ++n) _Pragma("unroll") for (int k = 0; k < 2; ++k) dst[n][k] = *(const PG8_LAS bf16x8*)(lds + PG8_SB(b, h) + boff + n * 2048 + k * 1024); } while (0)
; #define PG8_MMA(ai, bj, At, Bt) do { __builtin_amdgcn_s_setprio(1); _Pragma("unroll") for (int m = 0; m < 4; ++m) _Pragma("unroll") for (int n = 0; n < 2; ++n) _Pragma("unroll") for (int k = 0; k < 2; ++k) \
;         acc[ai][bj][m][n] = __builtin_amdgcn_mfma_f32_16x16x32_bf16(Bt[n][k], At[m][k], acc[ai][bj][m][n], 0, 0, 0); __builtin_amdgcn_s_setprio(0); } while (0)
; #define PG8_WAIT_V(n) asm volatile("s_waitcnt vmcnt(" #n ")" ::: "memory")
; #define PG8_WAIT_L(n) asm volatile("s_waitcnt lgkmcnt(" #n ")" ::: "memory")
; #define PG8_BAR __builtin_amdgcn_s_barrier()
; #define PG8_SCHED __builtin_amdgcn_sched_barrier(0)
; template <class Epi, class Sched, bool ALIGN_EPI = false, bool SP2 = false>
; __device__ __forceinline__ void gemm_phase(PG8_LAS unsigned char* lds, const Gemm g, const Sched& S, const Epi& E) {
;     ...
;             PG8_LDB(B0, 1, 0); PG8_LDB(B1, 1, 1); PG8_SCHED; PG8_LDA(At, 1, 0); PG8_STAGE(PG8_SA(0, 1), a2 + hstep, voffA);
;             PG8_WAIT_V(8); PG8_WAIT_L(0); PG8_BAR; PG8_MMA(0, 0, At, B0); PG8_MMA(0, 1, At, B1); PG8_BAR; PG8_SCHED;
;             PG8_LDA(At, 1, 1); PG8_STAGE(PG8_SB(1, 0), b3, voffB); PG8_STAGE(PG8_SB(1, 1), b3 + hstep, voffB); PG8_STAGE(PG8_SA(1, 0), a3, voffA);
;             PG8_WAIT_V(8); PG8_WAIT_L(0); PG8_BAR; PG8_MMA(1, 0, At, B0); PG8_MMA(1, 1, At, B1); PG8_BAR; PG8_SCHED;
	s_add_i32 s64, 0, 0x18000
	s_add_i32 s65, 0, 0x1c000
	v_add_u32_e32 v144, s64, v173
	v_add_u32_e32 v164, s65, v173
	ds_read_b128 v[132:135], v144
	ds_read_b128 v[136:139], v144 offset:1024
	ds_read_b128 v[140:143], v144 offset:2048
	ds_read_b128 v[144:147], v144 offset:3072
	ds_read_b128 v[158:161], v164
	ds_read_b128 v[174:177], v164 offset:1024
	ds_read_b128 v[206:209], v164 offset:2048
	ds_read_b128 v[210:213], v164 offset:3072
	s_add_u32 s100, s44, 0x80
	s_addc_u32 s101, s45, 0
	s_add_u32 s44, s44, 0x80000
	s_addc_u32 s45, s45, 0
	s_mov_b32 m0, s52
	ds_read_b128 v[214:217], v204 offset:32768
	ds_read_b128 v[218:221], v204 offset:33792
	ds_read_b128 v[222:225], v204 offset:34816
	ds_read_b128 v[226:229], v204 offset:35840
	ds_read_b128 v[230:233], v204 offset:36864
	ds_read_b128 v[234:237], v204 offset:37888
	ds_read_b128 v[238:241], v204 offset:38912
	ds_read_b128 v[242:245], v204 offset:39936
	global_load_lds_dwordx4 v152, s[44:45]
	s_waitcnt vmcnt(7)
	s_waitcnt lgkmcnt(0)
	s_barrier
	s_setprio 0
	s_waitcnt lgkmcnt(0)
	v_mfma_f32_16x16x32_bf16 v[128:131], v[132:135], v[214:217], v[128:131]
	v_mfma_f32_16x16x32_bf16 v[124:127], v[140:143], v[214:217], v[124:127]
	v_mfma_f32_16x16x32_bf16 v[116:119], v[132:135], v[222:225], v[116:119]
	s_mov_b32 m0, s53
	v_mfma_f32_16x16x32_bf16 v[108:111], v[140:143], v[222:225], v[108:111]
	global_load_lds_dwordx4 v150, s[44:45]
	v_mfma_f32_16x16x32_bf16 v[100:103], v[132:135], v[230:233], v[100:103]
	v_mfma_f32_16x16x32_bf16 v[92:95], v[140:143], v[230:233], v[92:95]
	v_mfma_f32_16x16x32_bf16 v[84:87], v[132:135], v[238:241], v[84:87]
	v_mfma_f32_16x16x32_bf16 v[76:79], v[140:143], v[238:241], v[76:79]
	v_mfma_f32_16x16x32_bf16 v[128:131], v[136:139], v[218:221], v[128:131]
	v_mfma_f32_16x16x32_bf16 v[124:127], v[144:147], v[218:221], v[124:127]
	v_mfma_f32_16x16x32_bf16 v[116:119], v[136:139], v[226:229], v[116:119]
	v_mfma_f32_16x16x32_bf16 v[108:111], v[144:147], v[226:229], v[108:111]
	v_mfma_f32_16x16x32_bf16 v[100:103], v[136:139], v[234:237], v[100:103]
	v_mfma_f32_16x16x32_bf16 v[92:95], v[144:147], v[234:237], v[92:95]
	v_mfma_f32_16x16x32_bf16 v[84:87], v[136:139], v[242:245], v[84:87]
	v_mfma_f32_16x16x32_bf16 v[76:79], v[144:147], v[242:245], v[76:79]
	s_setprio 1
	s_setprio 0
	v_mfma_f32_16x16x32_bf16 v[120:123], v[158:161], v[214:217], v[120:123]
	v_mfma_f32_16x16x32_bf16 v[112:115], v[206:209], v[214:217], v[112:115]
	v_mfma_f32_16x16x32_bf16 v[104:107], v[158:161], v[222:225], v[104:107]
	v_mfma_f32_16x16x32_bf16 v[96:99], v[206:209], v[222:225], v[96:99]
	v_mfma_f32_16x16x32_bf16 v[88:91], v[158:161], v[230:233], v[88:91]
	v_mfma_f32_16x16x32_bf16 v[80:83], v[206:209], v[230:233], v[80:83]
	v_mfma_f32_16x16x32_bf16 v[72:75], v[158:161], v[238:241], v[72:75]
	v_mfma_f32_16x16x32_bf16 v[68:71], v[206:209], v[238:241], v[68:71]
	v_mfma_f32_16x16x32_bf16 v[120:123], v[174:177], v[218:221], v[120:123]
	v_mfma_f32_16x16x32_bf16 v[112:115], v[210:213], v[218:221], v[112:115]
	v_mfma_f32_16x16x32_bf16 v[104:107], v[174:177], v[226:229], v[104:107]
	v_mfma_f32_16x16x32_bf16 v[96:99], v[210:213], v[226:229], v[96:99]
	v_mfma_f32_16x16x32_bf16 v[88:91], v[174:177], v[234:237], v[88:91]
	v_mfma_f32_16x16x32_bf16 v[80:83], v[210:213], v[234:237], v[80:83]
	v_mfma_f32_16x16x32_bf16 v[72:75], v[174:177], v[242:245], v[72:75]
	v_mfma_f32_16x16x32_bf16 v[68:71], v[210:213], v[242:245], v[68:71]
	s_setprio 1
	s_barrier
	s_add_i32 s44, s64, s46
	s_add_i32 m0, s44, 0xffffff80
	ds_read_b128 v[214:217], v204 offset:49152
	ds_read_b128 v[218:221], v204 offset:50176
	ds_read_b128 v[222:225], v204 offset:51200
	ds_read_b128 v[226:229], v204 offset:52224
	ds_read_b128 v[230:233], v204 offset:53248
	ds_read_b128 v[234:237], v204 offset:54272
	ds_read_b128 v[238:241], v204 offset:55296
	ds_read_b128 v[242:245], v204 offset:56320
	global_load_lds_dwordx4 v2, s[42:43] offset:128
	s_add_i32 m0, s44, 0x1f80
	s_add_i32 s44, s65, s46
	global_load_lds_dwordx4 v148, s[42:43] offset:128
	s_add_u32 s42, s42, 0x80080
	s_addc_u32 s43, s43, 0
	s_mov_b32 m0, s44
	s_nop 0
	global_load_lds_dwordx4 v2, s[42:43]
	s_add_i32 m0, s44, 0x2000
	s_nop 0
	global_load_lds_dwordx4 v148, s[42:43]
	s_waitcnt vmcnt(6)
	s_waitcnt lgkmcnt(0)
	s_barrier
	s_setprio 0
	s_waitcnt lgkmcnt(0)
	v_mfma_f32_16x16x32_bf16 v[64:67], v[132:135], v[214:217], v[64:67]
	v_mfma_f32_16x16x32_bf16 v[60:63], v[140:143], v[214:217], v[60:63]
	v_mfma_f32_16x16x32_bf16 v[52:55], v[132:135], v[222:225], v[52:55]
	s_mov_b32 m0, s54
	v_mfma_f32_16x16x32_bf16 v[44:47], v[140:143], v[222:225], v[44:47]
	global_load_lds_dwordx4 v152, s[100:101]
	v_mfma_f32_16x16x32_bf16 v[36:39], v[132:135], v[230:233], v[36:39]
	v_mfma_f32_16x16x32_bf16 v[28:31], v[140:143], v[230:233], v[28:31]
	v_mfma_f32_16x16x32_bf16 v[20:23], v[132:135], v[238:241], v[20:23]
	v_mfma_f32_16x16x32_bf16 v[12:15], v[140:143], v[238:241], v[12:15]
	v_mfma_f32_16x16x32_bf16 v[64:67], v[136:139], v[218:221], v[64:67]
	v_mfma_f32_16x16x32_bf16 v[60:63], v[144:147], v[218:221], v[60:63]
	v_mfma_f32_16x16x32_bf16 v[52:55], v[136:139], v[226:229], v[52:55]
	s_mov_b32 m0, s55
	v_mfma_f32_16x16x32_bf16 v[44:47], v[144:147], v[226:229], v[44:47]
	global_load_lds_dwordx4 v150, s[100:101]
	v_mfma_f32_16x16x32_bf16 v[36:39], v[136:139], v[234:237], v[36:39]
	v_mfma_f32_16x16x32_bf16 v[28:31], v[144:147], v[234:237], v[28:31]
	v_mfma_f32_16x16x32_bf16 v[20:23], v[136:139], v[242:245], v[20:23]
	v_mfma_f32_16x16x32_bf16 v[12:15], v[144:147], v[242:245], v[12:15]
	s_setprio 1
	s_setprio 0
	v_mfma_f32_16x16x32_bf16 v[56:59], v[158:161], v[214:217], v[56:59]
	v_mfma_f32_16x16x32_bf16 v[48:51], v[206:209], v[214:217], v[48:51]
	v_mfma_f32_16x16x32_bf16 v[40:43], v[158:161], v[222:225], v[40:43]
	v_mfma_f32_16x16x32_bf16 v[32:35], v[206:209], v[222:225], v[32:35]
	v_mfma_f32_16x16x32_bf16 v[24:27], v[158:161], v[230:233], v[24:27]
	v_mfma_f32_16x16x32_bf16 v[16:19], v[206:209], v[230:233], v[16:19]
	v_mfma_f32_16x16x32_bf16 v[8:11], v[158:161], v[238:241], v[8:11]
	v_mfma_f32_16x16x32_bf16 v[4:7], v[206:209], v[238:241], v[4:7]
	v_mfma_f32_16x16x32_bf16 v[56:59], v[174:177], v[218:221], v[56:59]
	v_mfma_f32_16x16x32_bf16 v[48:51], v[210:213], v[218:221], v[48:51]
	v_mfma_f32_16x16x32_bf16 v[40:43], v[174:177], v[226:229], v[40:43]
	v_mfma_f32_16x16x32_bf16 v[32:35], v[210:213], v[226:229], v[32:35]
	v_mfma_f32_16x16x32_bf16 v[24:27], v[174:177], v[234:237], v[24:27]
	v_mfma_f32_16x16x32_bf16 v[16:19], v[210:213], v[234:237], v[16:19]
	v_mfma_f32_16x16x32_bf16 v[8:11], v[174:177], v[242:245], v[8:11]
	v_mfma_f32_16x16x32_bf16 v[4:7], v[210:213], v[242:245], v[4:7]
	s_setprio 1
	s_barrier
	s_add_i32 s63, s63, 2
	s_add_u32 s40, s40, 0x100
	s_addc_u32 s41, s41, 0
	s_add_u32 s35, s35, 0x100
	s_addc_u32 s62, s62, 0
	s_cmp_gt_u32 s63, 29
	s_cbranch_scc0 .LBB0_674
	s_and_b64 vcc, exec, s[30:31]
	s_cbranch_vccz .LBB0_677
	s_barrier

; #define PG8_STAGE(bufoff, gbase, voff) do { _Pragma("unroll") for (int _i = 0; _i < 2; ++_i) \
;         __builtin_amdgcn_global_load_lds((const unsigned*)((const char*)(gbase) + (voff)[_i]), (PG8_LAS unsigned*)(lds + (bufoff) + ldsw + _i * 8192), 16, 0, 0); } while (0)
; #define PG8_LDA(dst, b, h) do { _Pragma("unroll") for (int m = 0; m < 4; ++m) _Pragma("unroll") for (int k = 0; k < 2; ++k) dst[m][k] = *(const PG8_LAS bf16x8*)(lds + PG8_SA(b, h) + aoff + m * 2048 + k * 1024); } while (0)
; #define PG8_LDB(dst, b, h) do { _Pragma("unroll") for (int n = 0; n < 2; ++n) _Pragma("unroll") for (int k = 0; k < 2; ++k) dst[n][k] = *(const PG8_LAS bf16x8*)(lds + PG8_SB(b, h) + boff + n * 2048 + k * 1024); } while (0)
; #define PG8_MMA(ai, bj, At, Bt) do { __builtin_amdgcn_s_setprio(1); _Pragma("unroll") for (int m = 0; m < 4; ++m) _Pragma("unroll") for (int n = 0; n < 2; ++n) _Pragma("unroll") for (int k = 0; k < 2; ++k) \
;         acc[ai][bj][m][n] = __builtin_amdgcn_mfma_f32_16x16x32_bf16(Bt[n][k], At[m][k], acc[ai][bj][m][n], 0, 0, 0); __builtin_amdgcn_s_setprio(0); } while (0)
; #define PG8_WAIT_V(n) asm volatile("s_waitcnt vmcnt(" #n ")" ::: "memory")
; #define PG8_BAR __builtin_amdgcn_s_barrier()
; template <class Epi, class Sched, bool ALIGN_EPI = false, bool SP2 = false>
; __device__ __forceinline__ void gemm_phase(PG8_LAS unsigned char* lds, const Gemm g, const Sched& S, const Epi& E) {
;     ...
;         for (int t = 0; t < nt; t += 2) {
;             const bool last = (t == nt - 2);
;             const char* a1 = cA + (size_t)(t + 1) * kstep;
;             const char* a2 = last ? nA : cA + (size_t)(t + 2) * kstep; const char* b2 = last ? nB : cB + (size_t)(t + 2) * kstep;
;             const char* a3 = a2 + kstep; const char* b3 = b2 + kstep;
;             if (last && has_next) S.a_ready(nxt);
;             if constexpr (SP2) {
;             PG8_LDB(B0, 0, 0); PG8_LDB(B1, 0, 1); PG8_SCHED; PG8_LDA(At, 0, 0); PG8_STAGE(PG8_SA(1, 1), a1 + hstep, voffA);
;             PG8_WAIT_V(8); PG8_WAIT_L(0); PG8_BAR; PG8_MMA(0, 0, At, B0); PG8_MMA(0, 1, At, B1); PG8_BAR; PG8_SCHED;
;             PG8_LDA(At, 0, 1); PG8_STAGE(PG8_SB(0, 0), b2, voffB); PG8_STAGE(PG8_SB(0, 1), b2 + hstep, voffB); PG8_STAGE(PG8_SA(0, 0), a2, voffA);
;             PG8_WAIT_V(8); PG8_WAIT_L(0); PG8_BAR; PG8_MMA(1, 0, At, B0); PG8_MMA(1, 1, At, B1); PG8_BAR; PG8_SCHED;
.LBB0_2096:
	s_add_u32 s27, s40, 0xfffc0080
	s_addc_u32 s29, s41, -1
	s_add_i32 s31, 0, 0x10000
	s_cmp_eq_u32 s26, 12
	s_cselect_b32 s45, s1, s29
	s_cselect_b32 s44, s0, s27
	v_add_u32_e32 v2, s31, v173
	s_cselect_b32 s43, s35, s13
	s_cselect_b32 s42, s34, s11
	s_add_i32 s27, 0, 0x14000
	ds_read_b128 v[134:137], v2
	ds_read_b128 v[138:141], v2 offset:1024
	ds_read_b128 v[154:157], v2 offset:2048
	ds_read_b128 v[158:161], v2 offset:3072
	v_add_u32_e32 v2, s27, v173
	ds_read_b128 v[178:181], v2
	ds_read_b128 v[204:207], v2 offset:1024
	ds_read_b128 v[208:211], v2 offset:2048
	ds_read_b128 v[212:215], v2 offset:3072
	s_add_i32 m0, s55, 0xc000
	ds_read_b128 v[216:219], v177
	ds_read_b128 v[220:223], v177 offset:1024
	ds_read_b128 v[224:227], v177 offset:2048
	ds_read_b128 v[228:231], v177 offset:3072
	ds_read_b128 v[232:235], v177 offset:4096
	ds_read_b128 v[236:239], v177 offset:5120
	ds_read_b128 v[240:243], v177 offset:6144
	ds_read_b128 v[244:247], v177 offset:7168
	global_load_lds_dwordx4 v150, s[40:41]
	s_nop 0
	s_waitcnt vmcnt(7)
	s_waitcnt lgkmcnt(0)
	s_barrier
	s_setprio 0
	s_waitcnt lgkmcnt(0)
	v_mfma_f32_16x16x32_bf16 v[130:133], v[134:137], v[216:219], v[130:133]
	v_mfma_f32_16x16x32_bf16 v[126:129], v[154:157], v[216:219], v[126:129]
	v_mfma_f32_16x16x32_bf16 v[122:125], v[134:137], v[224:227], v[122:125]
	s_add_i32 m0, s55, 0xe000
	v_mfma_f32_16x16x32_bf16 v[118:121], v[154:157], v[224:227], v[118:121]
	global_load_lds_dwordx4 v152, s[40:41]
	v_mfma_f32_16x16x32_bf16 v[114:117], v[134:137], v[232:235], v[114:117]
	v_mfma_f32_16x16x32_bf16 v[110:113], v[154:157], v[232:235], v[110:113]
	v_mfma_f32_16x16x32_bf16 v[106:109], v[134:137], v[240:243], v[106:109]
	v_mfma_f32_16x16x32_bf16 v[102:105], v[154:157], v[240:243], v[102:105]
	v_mfma_f32_16x16x32_bf16 v[130:133], v[138:141], v[220:223], v[130:133]
	v_mfma_f32_16x16x32_bf16 v[126:129], v[158:161], v[220:223], v[126:129]
	v_mfma_f32_16x16x32_bf16 v[122:125], v[138:141], v[228:231], v[122:125]
	v_mfma_f32_16x16x32_bf16 v[118:121], v[158:161], v[228:231], v[118:121]
	v_mfma_f32_16x16x32_bf16 v[114:117], v[138:141], v[236:239], v[114:117]
	v_mfma_f32_16x16x32_bf16 v[110:113], v[158:161], v[236:239], v[110:113]
	v_mfma_f32_16x16x32_bf16 v[106:109], v[138:141], v[244:247], v[106:109]
	v_mfma_f32_16x16x32_bf16 v[102:105], v[158:161], v[244:247], v[102:105]
	s_setprio 1
	s_setprio 0
	v_mfma_f32_16x16x32_bf16 v[98:101], v[178:181], v[216:219], v[98:101]
	v_mfma_f32_16x16x32_bf16 v[94:97], v[208:211], v[216:219], v[94:97]
	v_mfma_f32_16x16x32_bf16 v[90:93], v[178:181], v[224:227], v[90:93]
	v_mfma_f32_16x16x32_bf16 v[86:89], v[208:211], v[224:227], v[86:89]
	v_mfma_f32_16x16x32_bf16 v[82:85], v[178:181], v[232:235], v[82:85]
	v_mfma_f32_16x16x32_bf16 v[78:81], v[208:211], v[232:235], v[78:81]
	v_mfma_f32_16x16x32_bf16 v[74:77], v[178:181], v[240:243], v[74:77]
	v_mfma_f32_16x16x32_bf16 v[70:73], v[208:211], v[240:243], v[70:73]
	v_mfma_f32_16x16x32_bf16 v[98:101], v[204:207], v[220:223], v[98:101]
	v_mfma_f32_16x16x32_bf16 v[94:97], v[212:215], v[220:223], v[94:97]
	v_mfma_f32_16x16x32_bf16 v[90:93], v[204:207], v[228:231], v[90:93]
	v_mfma_f32_16x16x32_bf16 v[86:89], v[212:215], v[228:231], v[86:89]
	v_mfma_f32_16x16x32_bf16 v[82:85], v[204:207], v[236:239], v[82:85]
	v_mfma_f32_16x16x32_bf16 v[78:81], v[212:215], v[236:239], v[78:81]
	v_mfma_f32_16x16x32_bf16 v[74:77], v[204:207], v[244:247], v[74:77]
	v_mfma_f32_16x16x32_bf16 v[70:73], v[212:215], v[244:247], v[70:73]
	s_setprio 1
	s_barrier
	s_add_i32 s29, s31, s54
	s_mov_b32 m0, s29
	ds_read_b128 v[216:219], v177 offset:16384
	ds_read_b128 v[220:223], v177 offset:17408
	ds_read_b128 v[224:227], v177 offset:18432
	ds_read_b128 v[228:231], v177 offset:19456
	ds_read_b128 v[232:235], v177 offset:20480
	ds_read_b128 v[236:239], v177 offset:21504
	ds_read_b128 v[240:243], v177 offset:22528
	ds_read_b128 v[244:247], v177 offset:23552
	global_load_lds_dwordx4 v144, s[42:43]
	s_add_i32 m0, s29, 0x2000
	s_add_u32 s64, s42, 0x40000
	s_addc_u32 s65, s43, 0
	s_add_i32 s27, s27, s54
	global_load_lds_dwordx4 v148, s[42:43]
	s_mov_b32 m0, s27
	s_nop 0
	global_load_lds_dwordx4 v144, s[64:65]
	s_add_i32 m0, s27, 0x2000
	s_nop 0
	global_load_lds_dwordx4 v148, s[64:65]
	s_nop 0
	s_nop 0
	s_nop 0
	s_nop 0
	s_nop 0
	s_nop 0
	s_nop 0
	s_waitcnt vmcnt(6)
	s_waitcnt lgkmcnt(0)
	s_barrier
	s_setprio 0
	s_waitcnt lgkmcnt(0)
	v_mfma_f32_16x16x32_bf16 v[66:69], v[134:137], v[216:219], v[66:69]
	v_mfma_f32_16x16x32_bf16 v[62:65], v[154:157], v[216:219], v[62:65]
	v_mfma_f32_16x16x32_bf16 v[58:61], v[134:137], v[224:227], v[58:61]
	s_mov_b32 m0, s55
	v_mfma_f32_16x16x32_bf16 v[54:57], v[154:157], v[224:227], v[54:57]
	global_load_lds_dwordx4 v142, s[44:45]
	v_mfma_f32_16x16x32_bf16 v[50:53], v[134:137], v[232:235], v[50:53]
	v_mfma_f32_16x16x32_bf16 v[46:49], v[154:157], v[232:235], v[46:49]
	v_mfma_f32_16x16x32_bf16 v[42:45], v[134:137], v[240:243], v[42:45]
	v_mfma_f32_16x16x32_bf16 v[38:41], v[154:157], v[240:243], v[38:41]
	v_mfma_f32_16x16x32_bf16 v[66:69], v[138:141], v[220:223], v[66:69]
	v_mfma_f32_16x16x32_bf16 v[62:65], v[158:161], v[220:223], v[62:65]
	v_mfma_f32_16x16x32_bf16 v[58:61], v[138:141], v[228:231], v[58:61]
	s_mov_b32 m0, s56
	v_mfma_f32_16x16x32_bf16 v[54:57], v[158:161], v[228:231], v[54:57]
	global_load_lds_dwordx4 v146, s[44:45]
	v_mfma_f32_16x16x32_bf16 v[50:53], v[138:141], v[236:239], v[50:53]
	v_mfma_f32_16x16x32_bf16 v[46:49], v[158:161], v[236:239], v[46:49]
	v_mfma_f32_16x16x32_bf16 v[42:45], v[138:141], v[244:247], v[42:45]
	v_mfma_f32_16x16x32_bf16 v[38:41], v[158:161], v[244:247], v[38:41]
	s_setprio 1
	s_setprio 0
	v_mfma_f32_16x16x32_bf16 v[34:37], v[178:181], v[216:219], v[34:37]
	v_mfma_f32_16x16x32_bf16 v[30:33], v[208:211], v[216:219], v[30:33]
	v_mfma_f32_16x16x32_bf16 v[26:29], v[178:181], v[224:227], v[26:29]
	v_mfma_f32_16x16x32_bf16 v[22:25], v[208:211], v[224:227], v[22:25]
	v_mfma_f32_16x16x32_bf16 v[18:21], v[178:181], v[232:235], v[18:21]
	v_mfma_f32_16x16x32_bf16 v[14:17], v[208:211], v[232:235], v[14:17]
	v_mfma_f32_16x16x32_bf16 v[10:13], v[178:181], v[240:243], v[10:13]
	v_mfma_f32_16x16x32_bf16 v[4:7], v[208:211], v[240:243], v[6:9]
	v_mfma_f32_16x16x32_bf16 v[34:37], v[204:207], v[220:223], v[34:37]
	v_mfma_f32_16x16x32_bf16 v[30:33], v[212:215], v[220:223], v[30:33]
	v_mfma_f32_16x16x32_bf16 v[26:29], v[204:207], v[228:231], v[26:29]
	v_mfma_f32_16x16x32_bf16 v[22:25], v[212:215], v[228:231], v[22:25]
	v_mfma_f32_16x16x32_bf16 v[18:21], v[204:207], v[236:239], v[18:21]
	v_mfma_f32_16x16x32_bf16 v[14:17], v[212:215], v[236:239], v[14:17]
	v_mfma_f32_16x16x32_bf16 v[10:13], v[204:207], v[244:247], v[10:13]
	v_mfma_f32_16x16x32_bf16 v[4:7], v[212:215], v[244:247], v[4:7]
	s_setprio 1
	s_barrier
; #define PG8_STAGE(bufoff, gbase, voff) do { _Pragma("unroll") for (int _i = 0; _i < 2; ++_i) \
;         __builtin_amdgcn_global_load_lds((const unsigned*)((const char*)(gbase) + (voff)[_i]), (PG8_LAS unsigned*)(lds + (bufoff) + ldsw + _i * 8192), 16, 0, 0); } while (0)
; #define PG8_LDA(dst, b, h) do { _Pragma("unroll") for (int m = 0; m < 4; ++m) _Pragma("unroll") for (int k = 0; k < 2; ++k) dst[m][k] = *(const PG8_LAS bf16x8*)(lds + PG8_SA(b, h) + aoff + m * 2048 + k * 1024); } while (0)
; #define PG8_LDB(dst, b, h) do { _Pragma("unroll") for (int n = 0; n < 2; ++n) _Pragma("unroll") for (int k = 0; k < 2; ++k) dst[n][k] = *(const PG8_LAS bf16x8*)(lds + PG8_SB(b, h) + boff + n * 2048 + k * 1024); } while (0)
; #define PG8_MMA(ai, bj, At, Bt) do { __builtin_amdgcn_s_setprio(1); _Pragma("unroll") for (int m = 0; m < 4; ++m) _Pragma("unroll") for (int n = 0; n < 2; ++n) _Pragma("unroll") for (int k = 0; k < 2; ++k) \
;         acc[ai][bj][m][n] = __builtin_amdgcn_mfma_f32_16x16x32_bf16(Bt[n][k], At[m][k], acc[ai][bj][m][n], 0, 0, 0); __builtin_amdgcn_s_setprio(0); } while (0)
; #define PG8_WAIT_V(n) asm volatile("s_waitcnt vmcnt(" #n ")" ::: "memory")
; #define PG8_WAIT_L(n) asm volatile("s_waitcnt lgkmcnt(" #n ")" ::: "memory")
; #define PG8_BAR __builtin_amdgcn_s_barrier()
; #define PG8_SCHED __builtin_amdgcn_sched_barrier(0)
; template <class Epi, class Sched, bool ALIGN_EPI = false, bool SP2 = false>
; __device__ __forceinline__ void gemm_phase(PG8_LAS unsigned char* lds, const Gemm g, const Sched& S, const Epi& E) {
;     ...
;             PG8_LDB(B0, 1, 0); PG8_LDB(B1, 1, 1); PG8_SCHED; PG8_LDA(At, 1, 0); PG8_STAGE(PG8_SA(0, 1), a2 + hstep, voffA);
;             PG8_WAIT_V(8); PG8_WAIT_L(0); PG8_BAR; PG8_MMA(0, 0, At, B0); PG8_MMA(0, 1, At, B1); PG8_BAR; PG8_SCHED;
;             PG8_LDA(At, 1, 1); PG8_STAGE(PG8_SB(1, 0), b3, voffB); PG8_STAGE(PG8_SB(1, 1), b3 + hstep, voffB); PG8_STAGE(PG8_SA(1, 0), a3, voffA);
;             PG8_WAIT_V(8); PG8_WAIT_L(0); PG8_BAR; PG8_MMA(1, 0, At, B0); PG8_MMA(1, 1, At, B1); PG8_BAR; PG8_SCHED;
	s_add_i32 s27, 0, 0x18000
	v_add_u32_e32 v2, s27, v173
	s_add_i32 s29, 0, 0x1c000
	ds_read_b128 v[134:137], v2
	ds_read_b128 v[138:141], v2 offset:1024
	ds_read_b128 v[154:157], v2 offset:2048
	ds_read_b128 v[158:161], v2 offset:3072
	v_add_u32_e32 v2, s29, v173
	ds_read_b128 v[178:181], v2
	ds_read_b128 v[204:207], v2 offset:1024
	ds_read_b128 v[208:211], v2 offset:2048
	ds_read_b128 v[212:215], v2 offset:3072
	s_add_u32 s100, s44, 0x80
	s_addc_u32 s101, s45, 0
	s_add_u32 s44, s44, 0x40000
	s_addc_u32 s45, s45, 0
	s_mov_b32 m0, s57
	ds_read_b128 v[216:219], v177 offset:32768
	ds_read_b128 v[220:223], v177 offset:33792
	ds_read_b128 v[224:227], v177 offset:34816
	ds_read_b128 v[228:231], v177 offset:35840
	ds_read_b128 v[232:235], v177 offset:36864
	ds_read_b128 v[236:239], v177 offset:37888
	ds_read_b128 v[240:243], v177 offset:38912
	ds_read_b128 v[244:247], v177 offset:39936
	global_load_lds_dwordx4 v142, s[44:45]
	s_waitcnt vmcnt(7)
	s_waitcnt lgkmcnt(0)
	s_barrier
	s_setprio 0
	s_waitcnt lgkmcnt(0)
	v_mfma_f32_16x16x32_bf16 v[130:133], v[134:137], v[216:219], v[130:133]
	v_mfma_f32_16x16x32_bf16 v[126:129], v[154:157], v[216:219], v[126:129]
	v_mfma_f32_16x16x32_bf16 v[122:125], v[134:137], v[224:227], v[122:125]
	s_mov_b32 m0, s58
	v_mfma_f32_16x16x32_bf16 v[118:121], v[154:157], v[224:227], v[118:121]
	global_load_lds_dwordx4 v146, s[44:45]
	v_mfma_f32_16x16x32_bf16 v[114:117], v[134:137], v[232:235], v[114:117]
	v_mfma_f32_16x16x32_bf16 v[110:113], v[154:157], v[232:235], v[110:113]
	v_mfma_f32_16x16x32_bf16 v[106:109], v[134:137], v[240:243], v[106:109]
	v_mfma_f32_16x16x32_bf16 v[102:105], v[154:157], v[240:243], v[102:105]
	v_mfma_f32_16x16x32_bf16 v[130:133], v[138:141], v[220:223], v[130:133]
	v_mfma_f32_16x16x32_bf16 v[126:129], v[158:161], v[220:223], v[126:129]
	v_mfma_f32_16x16x32_bf16 v[122:125], v[138:141], v[228:231], v[122:125]
	v_mfma_f32_16x16x32_bf16 v[118:121], v[158:161], v[228:231], v[118:121]
	v_mfma_f32_16x16x32_bf16 v[114:117], v[138:141], v[236:239], v[114:117]
	v_mfma_f32_16x16x32_bf16 v[110:113], v[158:161], v[236:239], v[110:113]
	v_mfma_f32_16x16x32_bf16 v[106:109], v[138:141], v[244:247], v[106:109]
	v_mfma_f32_16x16x32_bf16 v[102:105], v[158:161], v[244:247], v[102:105]
	s_setprio 1
	s_setprio 0
	v_mfma_f32_16x16x32_bf16 v[98:101], v[178:181], v[216:219], v[98:101]
	v_mfma_f32_16x16x32_bf16 v[94:97], v[208:211], v[216:219], v[94:97]
	v_mfma_f32_16x16x32_bf16 v[90:93], v[178:181], v[224:227], v[90:93]
	v_mfma_f32_16x16x32_bf16 v[86:89], v[208:211], v[224:227], v[86:89]
	v_mfma_f32_16x16x32_bf16 v[82:85], v[178:181], v[232:235], v[82:85]
	v_mfma_f32_16x16x32_bf16 v[78:81], v[208:211], v[232:235], v[78:81]
	v_mfma_f32_16x16x32_bf16 v[74:77], v[178:181], v[240:243], v[74:77]
	v_mfma_f32_16x16x32_bf16 v[70:73], v[208:211], v[240:243], v[70:73]
	v_mfma_f32_16x16x32_bf16 v[98:101], v[204:207], v[220:223], v[98:101]
	v_mfma_f32_16x16x32_bf16 v[94:97], v[212:215], v[220:223], v[94:97]
	v_mfma_f32_16x16x32_bf16 v[90:93], v[204:207], v[228:231], v[90:93]
	v_mfma_f32_16x16x32_bf16 v[86:89], v[212:215], v[228:231], v[86:89]
	v_mfma_f32_16x16x32_bf16 v[82:85], v[204:207], v[236:239], v[82:85]
	v_mfma_f32_16x16x32_bf16 v[78:81], v[212:215], v[236:239], v[78:81]
	v_mfma_f32_16x16x32_bf16 v[74:77], v[204:207], v[244:247], v[74:77]
	v_mfma_f32_16x16x32_bf16 v[70:73], v[212:215], v[244:247], v[70:73]
	s_setprio 1
	s_barrier
	s_add_i32 s27, s27, s54
	s_add_i32 m0, s27, 0xffffff80
	ds_read_b128 v[216:219], v177 offset:49152
	ds_read_b128 v[220:223], v177 offset:50176
	ds_read_b128 v[224:227], v177 offset:51200
	ds_read_b128 v[228:231], v177 offset:52224
	ds_read_b128 v[232:235], v177 offset:53248
	ds_read_b128 v[236:239], v177 offset:54272
	ds_read_b128 v[240:243], v177 offset:55296
	ds_read_b128 v[244:247], v177 offset:56320
	global_load_lds_dwordx4 v144, s[42:43] offset:128
	s_add_i32 m0, s27, 0x1f80
	s_add_i32 s27, s29, s54
	global_load_lds_dwordx4 v148, s[42:43] offset:128
	s_add_u32 s42, s42, 0x40080
	s_addc_u32 s43, s43, 0
	s_mov_b32 m0, s27
	s_nop 0
	global_load_lds_dwordx4 v144, s[42:43]
	s_add_i32 m0, s27, 0x2000
	s_nop 0
	global_load_lds_dwordx4 v148, s[42:43]
	s_waitcnt vmcnt(6)
	s_waitcnt lgkmcnt(0)
	s_barrier
	s_setprio 0
	s_waitcnt lgkmcnt(0)
	v_mfma_f32_16x16x32_bf16 v[66:69], v[134:137], v[216:219], v[66:69]
	v_mfma_f32_16x16x32_bf16 v[62:65], v[154:157], v[216:219], v[62:65]
	v_mfma_f32_16x16x32_bf16 v[58:61], v[134:137], v[224:227], v[58:61]
	s_mov_b32 m0, s61
	v_mfma_f32_16x16x32_bf16 v[54:57], v[154:157], v[224:227], v[54:57]
	global_load_lds_dwordx4 v142, s[100:101]
	v_mfma_f32_16x16x32_bf16 v[50:53], v[134:137], v[232:235], v[50:53]
	v_mfma_f32_16x16x32_bf16 v[46:49], v[154:157], v[232:235], v[46:49]
	v_mfma_f32_16x16x32_bf16 v[42:45], v[134:137], v[240:243], v[42:45]
	v_mfma_f32_16x16x32_bf16 v[38:41], v[154:157], v[240:243], v[38:41]
	v_mfma_f32_16x16x32_bf16 v[66:69], v[138:141], v[220:223], v[66:69]
	v_mfma_f32_16x16x32_bf16 v[62:65], v[158:161], v[220:223], v[62:65]
	v_mfma_f32_16x16x32_bf16 v[58:61], v[138:141], v[228:231], v[58:61]
	s_mov_b32 m0, s62
	v_mfma_f32_16x16x32_bf16 v[54:57], v[158:161], v[228:231], v[54:57]
	global_load_lds_dwordx4 v146, s[100:101]
	v_mfma_f32_16x16x32_bf16 v[50:53], v[138:141], v[236:239], v[50:53]
	v_mfma_f32_16x16x32_bf16 v[46:49], v[158:161], v[236:239], v[46:49]
	v_mfma_f32_16x16x32_bf16 v[42:45], v[138:141], v[244:247], v[42:45]
	v_mfma_f32_16x16x32_bf16 v[38:41], v[158:161], v[244:247], v[38:41]
	s_setprio 1
	s_setprio 0
	v_mfma_f32_16x16x32_bf16 v[34:37], v[178:181], v[216:219], v[34:37]
	v_mfma_f32_16x16x32_bf16 v[30:33], v[208:211], v[216:219], v[30:33]
	v_mfma_f32_16x16x32_bf16 v[26:29], v[178:181], v[224:227], v[26:29]
	v_mfma_f32_16x16x32_bf16 v[22:25], v[208:211], v[224:227], v[22:25]
	v_mfma_f32_16x16x32_bf16 v[18:21], v[178:181], v[232:235], v[18:21]
	v_mfma_f32_16x16x32_bf16 v[14:17], v[208:211], v[232:235], v[14:17]
	v_mfma_f32_16x16x32_bf16 v[8:11], v[178:181], v[240:243], v[10:13]
	v_mfma_f32_16x16x32_bf16 v[4:7], v[208:211], v[240:243], v[4:7]
	v_mfma_f32_16x16x32_bf16 v[34:37], v[204:207], v[220:223], v[34:37]
	v_mfma_f32_16x16x32_bf16 v[30:33], v[212:215], v[220:223], v[30:33]
	v_mfma_f32_16x16x32_bf16 v[26:29], v[204:207], v[228:231], v[26:29]
	v_mfma_f32_16x16x32_bf16 v[22:25], v[212:215], v[228:231], v[22:25]
	v_mfma_f32_16x16x32_bf16 v[18:21], v[204:207], v[236:239], v[18:21]
	v_mfma_f32_16x16x32_bf16 v[14:17], v[212:215], v[236:239], v[14:17]
	v_mfma_f32_16x16x32_bf16 v[10:13], v[204:207], v[244:247], v[8:11]
	v_mfma_f32_16x16x32_bf16 v[6:9], v[212:215], v[244:247], v[4:7]
	s_setprio 1
	s_barrier
	s_add_i32 s26, s26, 2
	s_add_u32 s40, s40, 0x100
	s_addc_u32 s41, s41, 0
	s_add_u32 s11, s11, 0x100
	s_addc_u32 s13, s13, 0
	s_cmp_gt_u32 s26, 13
	s_cbranch_scc0 .LBB0_2096
	s_and_b64 vcc, exec, s[8:9]
	s_cbranch_vccz .LBB0_2099
	s_barrier

; #define PG8_STAGE(bufoff, gbase, voff) do { _Pragma("unroll") for (int _i = 0; _i < 2; ++_i) \
;         __builtin_amdgcn_global_load_lds((const unsigned*)((const char*)(gbase) + (voff)[_i]), (PG8_LAS unsigned*)(lds + (bufoff) + ldsw + _i * 8192), 16, 0, 0); } while (0)
; #define PG8_LDA(dst, b, h) do { _Pragma("unroll") for (int m = 0; m < 4; ++m) _Pragma("unroll") for (int k = 0; k < 2; ++k) dst[m][k] = *(const PG8_LAS bf16x8*)(lds + PG8_SA(b, h) + aoff + m * 2048 + k * 1024); } while (0)
; #define PG8_LDB(dst, b, h) do { _Pragma("unroll") for (int n = 0; n < 2; ++n) _Pragma("unroll") for (int k = 0; k < 2; ++k) dst[n][k] = *(const PG8_LAS bf16x8*)(lds + PG8_SB(b, h) + boff + n * 2048 + k * 1024); } while (0)
; #define PG8_MMA(ai, bj, At, Bt) do { __builtin_amdgcn_s_setprio(1); _Pragma("unroll") for (int m = 0; m < 4; ++m) _Pragma("unroll") for (int n = 0; n < 2; ++n) _Pragma("unroll") for (int k = 0; k < 2; ++k) \
;         acc[ai][bj][m][n] = __builtin_amdgcn_mfma_f32_16x16x32_bf16(Bt[n][k], At[m][k], acc[ai][bj][m][n], 0, 0, 0); __builtin_amdgcn_s_setprio(0); } while (0)
; #define PG8_WAIT_V(n) asm volatile("s_waitcnt vmcnt(" #n ")" ::: "memory")
; #define PG8_WAIT_L(n) asm volatile("s_waitcnt lgkmcnt(" #n ")" ::: "memory")
; #define PG8_BAR __builtin_amdgcn_s_barrier()
; #define PG8_SCHED __builtin_amdgcn_sched_barrier(0)
; template <class Epi, class Sched, bool ALIGN_EPI = false, bool SP2 = false>
; __device__ __forceinline__ void gemm_phase(PG8_LAS unsigned char* lds, const Gemm g, const Sched& S, const Epi& E) {
;     ...
;         for (int t = 0; t < nt; t += 2) {
;             const bool last = (t == nt - 2);
;             const char* a1 = cA + (size_t)(t + 1) * kstep;
;             const char* a2 = last ? nA : cA + (size_t)(t + 2) * kstep; const char* b2 = last ? nB : cB + (size_t)(t + 2) * kstep;
;             const char* a3 = a2 + kstep; const char* b3 = b2 + kstep;
;             if (last && has_next) S.a_ready(nxt);
;             if constexpr (SP2) {
;             PG8_LDB(B0, 0, 0); PG8_LDB(B1, 0, 1); PG8_SCHED; PG8_LDA(At, 0, 0); PG8_STAGE(PG8_SA(1, 1), a1 + hstep, voffA);
;             PG8_WAIT_V(8); PG8_WAIT_L(0); PG8_BAR; PG8_MMA(0, 0, At, B0); PG8_MMA(0, 1, At, B1); PG8_BAR; PG8_SCHED;
;             PG8_LDA(At, 0, 1); PG8_STAGE(PG8_SB(0, 0), b2, voffB); PG8_STAGE(PG8_SB(0, 1), b2 + hstep, voffB); PG8_STAGE(PG8_SA(0, 0), a2, voffA);
.LBB0_2185:
	s_add_u32 s42, s40, 0x100
	s_addc_u32 s43, s41, 0
	s_add_i32 s37, 0, 0x10000
	s_cmp_eq_u32 s31, 28
	s_cselect_b32 s47, s5, s43
	s_cselect_b32 s46, s4, s42
	v_add_u32_e32 v135, s37, v173
	s_cselect_b32 s45, s35, s29
	s_cselect_b32 s44, s34, s2
	s_add_i32 s39, 0, 0x14000
	ds_read_b128 v[142:145], v135
	ds_read_b128 v[146:149], v135 offset:1024
	ds_read_b128 v[150:153], v135 offset:2048
	ds_read_b128 v[154:157], v135 offset:3072
	v_add_u32_e32 v135, s39, v173
	ds_read_b128 v[158:161], v135
	ds_read_b128 v[174:177], v135 offset:1024
	ds_read_b128 v[180:183], v135 offset:2048
	ds_read_b128 v[204:207], v135 offset:3072
	v_lshl_add_u64 v[162:163], s[40:41], 0, v[138:139]
	s_add_i32 m0, s55, 0xc000
	ds_read_b128 v[208:211], v179
	ds_read_b128 v[212:215], v179 offset:1024
	ds_read_b128 v[216:219], v179 offset:2048
	ds_read_b128 v[220:223], v179 offset:3072
	ds_read_b128 v[224:227], v179 offset:4096
	ds_read_b128 v[228:231], v179 offset:5120
	ds_read_b128 v[232:235], v179 offset:6144
	ds_read_b128 v[236:239], v179 offset:7168
	global_load_lds_dwordx4 v[162:163], off
	v_lshl_add_u64 v[162:163], s[40:41], 0, v[140:141]
	s_nop 0
	s_waitcnt vmcnt(7)
	s_waitcnt lgkmcnt(0)
	s_barrier
	s_setprio 0
	s_waitcnt lgkmcnt(0)
	v_mfma_f32_16x16x32_bf16 v[128:131], v[142:145], v[208:211], v[128:131]
	v_mfma_f32_16x16x32_bf16 v[124:127], v[150:153], v[208:211], v[124:127]
	v_mfma_f32_16x16x32_bf16 v[112:115], v[142:145], v[216:219], v[112:115]
	s_add_i32 m0, s55, 0xe000
	v_mfma_f32_16x16x32_bf16 v[108:111], v[150:153], v[216:219], v[108:111]
	global_load_lds_dwordx4 v[162:163], off
	v_mfma_f32_16x16x32_bf16 v[96:99], v[142:145], v[224:227], v[96:99]
	v_mfma_f32_16x16x32_bf16 v[92:95], v[150:153], v[224:227], v[92:95]
	v_mfma_f32_16x16x32_bf16 v[80:83], v[142:145], v[232:235], v[80:83]
	v_mfma_f32_16x16x32_bf16 v[76:79], v[150:153], v[232:235], v[76:79]
	v_mfma_f32_16x16x32_bf16 v[128:131], v[146:149], v[212:215], v[128:131]
	v_mfma_f32_16x16x32_bf16 v[124:127], v[154:157], v[212:215], v[124:127]
	v_mfma_f32_16x16x32_bf16 v[112:115], v[146:149], v[220:223], v[112:115]
	v_mfma_f32_16x16x32_bf16 v[108:111], v[154:157], v[220:223], v[108:111]
	v_mfma_f32_16x16x32_bf16 v[96:99], v[146:149], v[228:231], v[96:99]
	v_mfma_f32_16x16x32_bf16 v[92:95], v[154:157], v[228:231], v[92:95]
	v_mfma_f32_16x16x32_bf16 v[80:83], v[146:149], v[236:239], v[80:83]
	v_mfma_f32_16x16x32_bf16 v[76:79], v[154:157], v[236:239], v[76:79]
	s_setprio 1
	s_setprio 0
	v_mfma_f32_16x16x32_bf16 v[120:123], v[158:161], v[208:211], v[120:123]
	v_mfma_f32_16x16x32_bf16 v[116:119], v[180:183], v[208:211], v[116:119]
	v_mfma_f32_16x16x32_bf16 v[104:107], v[158:161], v[216:219], v[104:107]
	v_mfma_f32_16x16x32_bf16 v[100:103], v[180:183], v[216:219], v[100:103]
	v_mfma_f32_16x16x32_bf16 v[88:91], v[158:161], v[224:227], v[88:91]
	v_mfma_f32_16x16x32_bf16 v[84:87], v[180:183], v[224:227], v[84:87]
	v_mfma_f32_16x16x32_bf16 v[72:75], v[158:161], v[232:235], v[72:75]
	v_mfma_f32_16x16x32_bf16 v[68:71], v[180:183], v[232:235], v[68:71]
	v_mfma_f32_16x16x32_bf16 v[120:123], v[174:177], v[212:215], v[120:123]
	v_mfma_f32_16x16x32_bf16 v[116:119], v[204:207], v[212:215], v[116:119]
	v_mfma_f32_16x16x32_bf16 v[104:107], v[174:177], v[220:223], v[104:107]
	v_mfma_f32_16x16x32_bf16 v[100:103], v[204:207], v[220:223], v[100:103]
	v_mfma_f32_16x16x32_bf16 v[88:91], v[174:177], v[228:231], v[88:91]
	v_mfma_f32_16x16x32_bf16 v[84:87], v[204:207], v[228:231], v[84:87]
	v_mfma_f32_16x16x32_bf16 v[72:75], v[174:177], v[236:239], v[72:75]
	v_mfma_f32_16x16x32_bf16 v[68:71], v[204:207], v[236:239], v[68:71]
	s_setprio 1
	s_barrier
	s_add_i32 s37, s37, s54
	s_mov_b32 m0, s37
	ds_read_b128 v[208:211], v179 offset:16384
	ds_read_b128 v[212:215], v179 offset:17408
	ds_read_b128 v[216:219], v179 offset:18432
	ds_read_b128 v[220:223], v179 offset:19456
	ds_read_b128 v[224:227], v179 offset:20480
	ds_read_b128 v[228:231], v179 offset:21504
	ds_read_b128 v[232:235], v179 offset:22528
	ds_read_b128 v[236:239], v179 offset:23552
	global_load_lds_dwordx4 v2, s[44:45]
	s_add_i32 m0, s37, 0x2000
	s_add_u32 s40, s44, 0x80000
	s_addc_u32 s41, s45, 0
	s_add_i32 s37, s39, s54
	global_load_lds_dwordx4 v132, s[44:45]
	s_mov_b32 m0, s37
	s_nop 0
	global_load_lds_dwordx4 v2, s[40:41]
	s_add_i32 m0, s37, 0x2000
	s_nop 0
	global_load_lds_dwordx4 v132, s[40:41]
	s_nop 0
	s_nop 0
	s_nop 0
	s_nop 0
	s_nop 0
	s_nop 0
	s_nop 0
	s_waitcnt vmcnt(6)
	s_waitcnt lgkmcnt(0)
	s_barrier
; #define PG8_STAGE(bufoff, gbase, voff) do { _Pragma("unroll") for (int _i = 0; _i < 2; ++_i) \
;         __builtin_amdgcn_global_load_lds((const unsigned*)((const char*)(gbase) + (voff)[_i]), (PG8_LAS unsigned*)(lds + (bufoff) + ldsw + _i * 8192), 16, 0, 0); } while (0)
; #define PG8_LDA(dst, b, h) do { _Pragma("unroll") for (int m = 0; m < 4; ++m) _Pragma("unroll") for (int k = 0; k < 2; ++k) dst[m][k] = *(const PG8_LAS bf16x8*)(lds + PG8_SA(b, h) + aoff + m * 2048 + k * 1024); } while (0)
; #define PG8_LDB(dst, b, h) do { _Pragma("unroll") for (int n = 0; n < 2; ++n) _Pragma("unroll") for (int k = 0; k < 2; ++k) dst[n][k] = *(const PG8_LAS bf16x8*)(lds + PG8_SB(b, h) + boff + n * 2048 + k * 1024); } while (0)
; #define PG8_MMA(ai, bj, At, Bt) do { __builtin_amdgcn_s_setprio(1); _Pragma("unroll") for (int m = 0; m < 4; ++m) _Pragma("unroll") for (int n = 0; n < 2; ++n) _Pragma("unroll") for (int k = 0; k < 2; ++k) \
;         acc[ai][bj][m][n] = __builtin_amdgcn_mfma_f32_16x16x32_bf16(Bt[n][k], At[m][k], acc[ai][bj][m][n], 0, 0, 0); __builtin_amdgcn_s_setprio(0); } while (0)
; #define PG8_WAIT_V(n) asm volatile("s_waitcnt vmcnt(" #n ")" ::: "memory")
; #define PG8_WAIT_L(n) asm volatile("s_waitcnt lgkmcnt(" #n ")" ::: "memory")
; #define PG8_BAR __builtin_amdgcn_s_barrier()
; #define PG8_SCHED __builtin_amdgcn_sched_barrier(0)
; template <class Epi, class Sched, bool ALIGN_EPI = false, bool SP2 = false>
; __device__ __forceinline__ void gemm_phase(PG8_LAS unsigned char* lds, const Gemm g, const Sched& S, const Epi& E) {
;     ...
;             PG8_LDA(At, 0, 1); PG8_STAGE(PG8_SB(0, 0), b2, voffB); PG8_STAGE(PG8_SB(0, 1), b2 + hstep, voffB); PG8_STAGE(PG8_SA(0, 0), a2, voffA);
;             PG8_WAIT_V(8); PG8_WAIT_L(0); PG8_BAR; PG8_MMA(1, 0, At, B0); PG8_MMA(1, 1, At, B1); PG8_BAR; PG8_SCHED;
;             PG8_LDB(B0, 1, 0); PG8_LDB(B1, 1, 1); PG8_SCHED; PG8_LDA(At, 1, 0); PG8_STAGE(PG8_SA(0, 1), a2 + hstep, voffA);
;             PG8_WAIT_V(8); PG8_WAIT_L(0); PG8_BAR; PG8_MMA(0, 0, At, B0); PG8_MMA(0, 1, At, B1); PG8_BAR; PG8_SCHED;
	s_setprio 0
	s_waitcnt lgkmcnt(0)
	v_mfma_f32_16x16x32_bf16 v[64:67], v[142:145], v[208:211], v[64:67]
	v_mfma_f32_16x16x32_bf16 v[60:63], v[150:153], v[208:211], v[60:63]
	v_mfma_f32_16x16x32_bf16 v[48:51], v[142:145], v[216:219], v[48:51]
	s_mov_b32 m0, s55
	v_mfma_f32_16x16x32_bf16 v[44:47], v[150:153], v[216:219], v[44:47]
	global_load_lds_dwordx4 v2, s[46:47]
	v_mfma_f32_16x16x32_bf16 v[32:35], v[142:145], v[224:227], v[32:35]
	v_mfma_f32_16x16x32_bf16 v[28:31], v[150:153], v[224:227], v[28:31]
	v_mfma_f32_16x16x32_bf16 v[16:19], v[142:145], v[232:235], v[16:19]
	v_mfma_f32_16x16x32_bf16 v[12:15], v[150:153], v[232:235], v[12:15]
	v_mfma_f32_16x16x32_bf16 v[64:67], v[146:149], v[212:215], v[64:67]
	v_mfma_f32_16x16x32_bf16 v[60:63], v[154:157], v[212:215], v[60:63]
	v_mfma_f32_16x16x32_bf16 v[48:51], v[146:149], v[220:223], v[48:51]
	s_mov_b32 m0, s56
	v_mfma_f32_16x16x32_bf16 v[44:47], v[154:157], v[220:223], v[44:47]
	global_load_lds_dwordx4 v132, s[46:47]
	v_mfma_f32_16x16x32_bf16 v[32:35], v[146:149], v[228:231], v[32:35]
	v_mfma_f32_16x16x32_bf16 v[28:31], v[154:157], v[228:231], v[28:31]
	v_mfma_f32_16x16x32_bf16 v[16:19], v[146:149], v[236:239], v[16:19]
	v_mfma_f32_16x16x32_bf16 v[12:15], v[154:157], v[236:239], v[12:15]
	s_setprio 1
	s_setprio 0
	v_mfma_f32_16x16x32_bf16 v[56:59], v[158:161], v[208:211], v[56:59]
	v_mfma_f32_16x16x32_bf16 v[52:55], v[180:183], v[208:211], v[52:55]
	v_mfma_f32_16x16x32_bf16 v[40:43], v[158:161], v[216:219], v[40:43]
	v_mfma_f32_16x16x32_bf16 v[36:39], v[180:183], v[216:219], v[36:39]
	v_mfma_f32_16x16x32_bf16 v[24:27], v[158:161], v[224:227], v[24:27]
	v_mfma_f32_16x16x32_bf16 v[20:23], v[180:183], v[224:227], v[20:23]
	v_mfma_f32_16x16x32_bf16 v[8:11], v[158:161], v[232:235], v[8:11]
	v_mfma_f32_16x16x32_bf16 v[4:7], v[180:183], v[232:235], v[4:7]
	v_mfma_f32_16x16x32_bf16 v[56:59], v[174:177], v[212:215], v[56:59]
	v_mfma_f32_16x16x32_bf16 v[52:55], v[204:207], v[212:215], v[52:55]
	v_mfma_f32_16x16x32_bf16 v[40:43], v[174:177], v[220:223], v[40:43]
	v_mfma_f32_16x16x32_bf16 v[36:39], v[204:207], v[220:223], v[36:39]
	v_mfma_f32_16x16x32_bf16 v[24:27], v[174:177], v[228:231], v[24:27]
	v_mfma_f32_16x16x32_bf16 v[20:23], v[204:207], v[228:231], v[20:23]
	v_mfma_f32_16x16x32_bf16 v[8:11], v[174:177], v[236:239], v[8:11]
	v_mfma_f32_16x16x32_bf16 v[4:7], v[204:207], v[236:239], v[4:7]
	s_setprio 1
	s_barrier
	s_add_i32 s37, 0, 0x18000
	v_add_u32_e32 v135, s37, v173
	s_add_i32 s39, 0, 0x1c000
	ds_read_b128 v[142:145], v135
	ds_read_b128 v[146:149], v135 offset:1024
	ds_read_b128 v[150:153], v135 offset:2048
	ds_read_b128 v[154:157], v135 offset:3072
	v_add_u32_e32 v135, s39, v173
	ds_read_b128 v[158:161], v135
	ds_read_b128 v[174:177], v135 offset:1024
	ds_read_b128 v[180:183], v135 offset:2048
	ds_read_b128 v[204:207], v135 offset:3072
	s_add_u32 s40, s46, 0x80000
	s_addc_u32 s41, s47, 0
	s_mov_b32 m0, s57
	ds_read_b128 v[208:211], v179 offset:32768
	ds_read_b128 v[212:215], v179 offset:33792
	ds_read_b128 v[216:219], v179 offset:34816
	ds_read_b128 v[220:223], v179 offset:35840
	ds_read_b128 v[224:227], v179 offset:36864
	ds_read_b128 v[228:231], v179 offset:37888
	ds_read_b128 v[232:235], v179 offset:38912
	ds_read_b128 v[236:239], v179 offset:39936
	global_load_lds_dwordx4 v2, s[40:41]
	s_waitcnt vmcnt(7)
	s_waitcnt lgkmcnt(0)
	s_barrier
	s_setprio 0
	s_waitcnt lgkmcnt(0)
	v_mfma_f32_16x16x32_bf16 v[128:131], v[142:145], v[208:211], v[128:131]
	v_mfma_f32_16x16x32_bf16 v[124:127], v[150:153], v[208:211], v[124:127]
	v_mfma_f32_16x16x32_bf16 v[112:115], v[142:145], v[216:219], v[112:115]
	s_mov_b32 m0, s58
	v_mfma_f32_16x16x32_bf16 v[108:111], v[150:153], v[216:219], v[108:111]
	global_load_lds_dwordx4 v132, s[40:41]
	v_mfma_f32_16x16x32_bf16 v[96:99], v[142:145], v[224:227], v[96:99]
	v_mfma_f32_16x16x32_bf16 v[92:95], v[150:153], v[224:227], v[92:95]
	v_mfma_f32_16x16x32_bf16 v[80:83], v[142:145], v[232:235], v[80:83]
	v_mfma_f32_16x16x32_bf16 v[76:79], v[150:153], v[232:235], v[76:79]
	v_mfma_f32_16x16x32_bf16 v[128:131], v[146:149], v[212:215], v[128:131]
	v_mfma_f32_16x16x32_bf16 v[124:127], v[154:157], v[212:215], v[124:127]
	v_mfma_f32_16x16x32_bf16 v[112:115], v[146:149], v[220:223], v[112:115]
	v_mfma_f32_16x16x32_bf16 v[108:111], v[154:157], v[220:223], v[108:111]
	v_mfma_f32_16x16x32_bf16 v[96:99], v[146:149], v[228:231], v[96:99]
	v_mfma_f32_16x16x32_bf16 v[92:95], v[154:157], v[228:231], v[92:95]
	v_mfma_f32_16x16x32_bf16 v[80:83], v[146:149], v[236:239], v[80:83]
	v_mfma_f32_16x16x32_bf16 v[76:79], v[154:157], v[236:239], v[76:79]
	s_setprio 1
	s_setprio 0
	v_mfma_f32_16x16x32_bf16 v[120:123], v[158:161], v[208:211], v[120:123]
	v_mfma_f32_16x16x32_bf16 v[116:119], v[180:183], v[208:211], v[116:119]
	v_mfma_f32_16x16x32_bf16 v[104:107], v[158:161], v[216:219], v[104:107]
	v_mfma_f32_16x16x32_bf16 v[100:103], v[180:183], v[216:219], v[100:103]
	v_mfma_f32_16x16x32_bf16 v[88:91], v[158:161], v[224:227], v[88:91]
	v_mfma_f32_16x16x32_bf16 v[84:87], v[180:183], v[224:227], v[84:87]
	v_mfma_f32_16x16x32_bf16 v[72:75], v[158:161], v[232:235], v[72:75]
	v_mfma_f32_16x16x32_bf16 v[68:71], v[180:183], v[232:235], v[68:71]
	v_mfma_f32_16x16x32_bf16 v[120:123], v[174:177], v[212:215], v[120:123]
	v_mfma_f32_16x16x32_bf16 v[116:119], v[204:207], v[212:215], v[116:119]
	v_mfma_f32_16x16x32_bf16 v[104:107], v[174:177], v[220:223], v[104:107]
	v_mfma_f32_16x16x32_bf16 v[100:103], v[204:207], v[220:223], v[100:103]
	v_mfma_f32_16x16x32_bf16 v[88:91], v[174:177], v[228:231], v[88:91]
	v_mfma_f32_16x16x32_bf16 v[84:87], v[204:207], v[228:231], v[84:87]
	v_mfma_f32_16x16x32_bf16 v[72:75], v[174:177], v[236:239], v[72:75]
	v_mfma_f32_16x16x32_bf16 v[68:71], v[204:207], v[236:239], v[68:71]
	s_setprio 1
	s_barrier
; #define PG8_STAGE(bufoff, gbase, voff) do { _Pragma("unroll") for (int _i = 0; _i < 2; ++_i) \
;         __builtin_amdgcn_global_load_lds((const unsigned*)((const char*)(gbase) + (voff)[_i]), (PG8_LAS unsigned*)(lds + (bufoff) + ldsw + _i * 8192), 16, 0, 0); } while (0)
; #define PG8_LDA(dst, b, h) do { _Pragma("unroll") for (int m = 0; m < 4; ++m) _Pragma("unroll") for (int k = 0; k < 2; ++k) dst[m][k] = *(const PG8_LAS bf16x8*)(lds + PG8_SA(b, h) + aoff + m * 2048 + k * 1024); } while (0)
; #define PG8_MMA(ai, bj, At, Bt) do { __builtin_amdgcn_s_setprio(1); _Pragma("unroll") for (int m = 0; m < 4; ++m) _Pragma("unroll") for (int n = 0; n < 2; ++n) _Pragma("unroll") for (int k = 0; k < 2; ++k) \
;         acc[ai][bj][m][n] = __builtin_amdgcn_mfma_f32_16x16x32_bf16(Bt[n][k], At[m][k], acc[ai][bj][m][n], 0, 0, 0); __builtin_amdgcn_s_setprio(0); } while (0)
; #define PG8_WAIT_V(n) asm volatile("s_waitcnt vmcnt(" #n ")" ::: "memory")
; #define PG8_WAIT_L(n) asm volatile("s_waitcnt lgkmcnt(" #n ")" ::: "memory")
; #define PG8_BAR __builtin_amdgcn_s_barrier()
; #define PG8_SCHED __builtin_amdgcn_sched_barrier(0)
; template <class Epi, class Sched, bool ALIGN_EPI = false, bool SP2 = false>
; __device__ __forceinline__ void gemm_phase(PG8_LAS unsigned char* lds, const Gemm g, const Sched& S, const Epi& E) {
;     ...
;             PG8_LDA(At, 1, 1); PG8_STAGE(PG8_SB(1, 0), b3, voffB); PG8_STAGE(PG8_SB(1, 1), b3 + hstep, voffB); PG8_STAGE(PG8_SA(1, 0), a3, voffA);
;             PG8_WAIT_V(8); PG8_WAIT_L(0); PG8_BAR; PG8_MMA(1, 0, At, B0); PG8_MMA(1, 1, At, B1); PG8_BAR; PG8_SCHED;
	s_add_i32 s37, s37, s54
	s_add_i32 m0, s37, 0xffffff80
	ds_read_b128 v[208:211], v179 offset:49152
	ds_read_b128 v[212:215], v179 offset:50176
	ds_read_b128 v[216:219], v179 offset:51200
	ds_read_b128 v[220:223], v179 offset:52224
	ds_read_b128 v[224:227], v179 offset:53248
	ds_read_b128 v[228:231], v179 offset:54272
	ds_read_b128 v[232:235], v179 offset:55296
	ds_read_b128 v[236:239], v179 offset:56320
	global_load_lds_dwordx4 v2, s[44:45] offset:128
	s_add_i32 m0, s37, 0x1f80
	s_add_u32 s40, s44, 0x80080
	s_addc_u32 s41, s45, 0
	s_add_i32 s37, s39, s54
	global_load_lds_dwordx4 v132, s[44:45] offset:128
	s_mov_b32 m0, s37
	s_nop 0
	global_load_lds_dwordx4 v2, s[40:41]
	s_add_i32 m0, s37, 0x2000
	s_nop 0
	global_load_lds_dwordx4 v132, s[40:41]
	s_waitcnt vmcnt(6)
	s_waitcnt lgkmcnt(0)
	s_barrier
	s_setprio 0
	s_waitcnt lgkmcnt(0)
	v_mfma_f32_16x16x32_bf16 v[64:67], v[142:145], v[208:211], v[64:67]
	v_mfma_f32_16x16x32_bf16 v[60:63], v[150:153], v[208:211], v[60:63]
	v_mfma_f32_16x16x32_bf16 v[48:51], v[142:145], v[216:219], v[48:51]
	s_add_i32 m0, s60, 0xffffff80
	v_mfma_f32_16x16x32_bf16 v[44:47], v[150:153], v[216:219], v[44:47]
	global_load_lds_dwordx4 v2, s[46:47] offset:128
	v_mfma_f32_16x16x32_bf16 v[32:35], v[142:145], v[224:227], v[32:35]
	v_mfma_f32_16x16x32_bf16 v[28:31], v[150:153], v[224:227], v[28:31]
	v_mfma_f32_16x16x32_bf16 v[16:19], v[142:145], v[232:235], v[16:19]
	v_mfma_f32_16x16x32_bf16 v[12:15], v[150:153], v[232:235], v[12:15]
	v_mfma_f32_16x16x32_bf16 v[64:67], v[146:149], v[212:215], v[64:67]
	v_mfma_f32_16x16x32_bf16 v[60:63], v[154:157], v[212:215], v[60:63]
	v_mfma_f32_16x16x32_bf16 v[48:51], v[146:149], v[220:223], v[48:51]
	s_add_i32 m0, s61, 0xffffff80
	v_mfma_f32_16x16x32_bf16 v[44:47], v[154:157], v[220:223], v[44:47]
	global_load_lds_dwordx4 v132, s[46:47] offset:128
	v_mfma_f32_16x16x32_bf16 v[32:35], v[146:149], v[228:231], v[32:35]
	v_mfma_f32_16x16x32_bf16 v[28:31], v[154:157], v[228:231], v[28:31]
	v_mfma_f32_16x16x32_bf16 v[16:19], v[146:149], v[236:239], v[16:19]
	v_mfma_f32_16x16x32_bf16 v[12:15], v[154:157], v[236:239], v[12:15]
	s_setprio 1
	s_setprio 0
	v_mfma_f32_16x16x32_bf16 v[56:59], v[158:161], v[208:211], v[56:59]
	v_mfma_f32_16x16x32_bf16 v[52:55], v[180:183], v[208:211], v[52:55]
	v_mfma_f32_16x16x32_bf16 v[40:43], v[158:161], v[216:219], v[40:43]
	v_mfma_f32_16x16x32_bf16 v[36:39], v[180:183], v[216:219], v[36:39]
	v_mfma_f32_16x16x32_bf16 v[24:27], v[158:161], v[224:227], v[24:27]
	v_mfma_f32_16x16x32_bf16 v[20:23], v[180:183], v[224:227], v[20:23]
	v_mfma_f32_16x16x32_bf16 v[8:11], v[158:161], v[232:235], v[8:11]
	v_mfma_f32_16x16x32_bf16 v[4:7], v[180:183], v[232:235], v[4:7]
	v_mfma_f32_16x16x32_bf16 v[56:59], v[174:177], v[212:215], v[56:59]
	v_mfma_f32_16x16x32_bf16 v[52:55], v[204:207], v[212:215], v[52:55]
	v_mfma_f32_16x16x32_bf16 v[40:43], v[174:177], v[220:223], v[40:43]
	v_mfma_f32_16x16x32_bf16 v[36:39], v[204:207], v[220:223], v[36:39]
	v_mfma_f32_16x16x32_bf16 v[24:27], v[174:177], v[228:231], v[24:27]
	v_mfma_f32_16x16x32_bf16 v[20:23], v[204:207], v[228:231], v[20:23]
	v_mfma_f32_16x16x32_bf16 v[8:11], v[174:177], v[236:239], v[8:11]
	v_mfma_f32_16x16x32_bf16 v[4:7], v[204:207], v[236:239], v[4:7]
	s_setprio 1
	s_barrier
	s_add_i32 s31, s31, 2
	s_add_u32 s2, s2, 0x100
	s_addc_u32 s29, s29, 0
	s_cmp_gt_u32 s31, 29
	s_mov_b64 s[40:41], s[42:43]
	s_cbranch_scc0 .LBB0_2185
	s_and_b64 vcc, exec, s[26:27]
	s_cbranch_vccz .LBB0_2188
	s_barrier
